# S5 pass-3 rewrite v3: time-major LDS layout (b128 Bu writes, addtid recurrence I/O, b128 C-proj reads), hoisted tables, cooperative carry loads
# speedup vs baseline: 1.0054x; 1.0034x over previous
; DI void s5_pass3_item(const Params& P, int bitem, unsigned char* smem) {
;     int tid_ = threadIdx.x; asm volatile("" : "+v"(tid_));
;     unsigned char* ws = P.ws; const int tid = tid_, wid = tid >> 6, lane = tid & 63, r = lane & 15, q = lane >> 4;
;     const int item = bitem * 8 + wid, ch = item & 31, grp = (item >> 5) & 63, b = item >> 11;
;     const bf16_t* proj = (const bf16_t*)(ws + WS_PROJ); const float* sm = (const float*)(ws + WS_SMALL);
;     float* xs = (float*)smem + wid * 2176;
;     bf16_t* HG = (bf16_t*)(ws + WS_HG);
;     const bf16_t* tb = (const bf16_t*)(sm + SM_BB);
;     bf16x8 af[8];
; #pragma unroll
;     for (int pt = 0; pt < 8; ++pt) af[pt] = *(const bf16x8*)(tb + (grp * 128 + 16 * pt + r) * 32 + 8 * q);
;     const f32x4 ab = *(const f32x4*)(sm + SM_AB + (grp * 64 + lane) * 4);
;     float cB[32];
;     { const float* cre = P.in[21] + (size_t)(grp * 16 + r) * 64; const float* cim = P.in[22] + (size_t)(grp * 16 + r) * 64;
; #pragma unroll
;       for (int i = 0; i < 32; ++i) { const int k = 4 * i + q; cB[i] = (i < 16) ? cre[k] : -cim[k - 64]; } }
;     const float dsk = P.in[23][grp * 16 + r];
;     const bf16_t* ubase = proj + (size_t)(b * TT + ch * 64) * NPROJ + C_SSM + grp * 16;
;     bf16x8 ubs[4]; unsigned short uvs[4][4];
; #pragma unroll
;     for (int sub = 0; sub < 4; ++sub) { ubs[sub] = *(const bf16x8*)(ubase + (size_t)(sub * 16 + r) * NPROJ + 8 * (q & 1));
; #pragma unroll
;         for (int j = 0; j < 4; ++j) uvs[sub][j] = ubase[(size_t)(sub * 16 + 4 * q + j) * NPROJ + r]; }
.Ls5n_start:
	v_lshrrev_b32_e32 v1, 6, v206
	v_and_b32_e32 v2, 63, v206
	v_readfirstlane_b32 s16, v1
	v_and_b32_e32 v3, 15, v206
	v_bfe_u32 v4, v206, 4, 2
	s_lshr_b32 s17, s88, 2
	s_and_b32 s18, s88, 3
	s_lshl_b32 s18, s18, 3
	s_add_i32 s18, s18, s16
	v_mov_b32_e32 v205, 0
	s_mul_i32 s0, s16, 0x2200
	s_mov_b32 m0, s0
	v_mul_u32_u24_e32 v5, 0x210, v3
	v_lshl_add_u32 v5, v4, 4, v5
	v_add_u32_e32 v77, s0, v5
	v_lshlrev_b32_e32 v5, 3, v206
	v_add_u32_e32 v81, 0x11000, v5
	v_add_u32_e32 v199, 0x1000, v5
	v_add_u32_e32 v204, 0x3000, v5
	v_lshlrev_b32_e32 v5, 3, v2
	v_add_u32_e32 v82, 0x11000, v5
	v_and_b32_e32 v5, 1, v4
	v_lshlrev_b32_e32 v5, 4, v5
	s_movk_i32 s1, 0x1e00
	v_mad_u32_u24 v83, v3, s1, v5
	v_lshlrev_b32_e32 v5, 2, v4
	v_lshlrev_b32_e32 v6, 1, v3
	v_mad_u32_u24 v84, v5, s1, v6
	v_add_u32_e32 v85, 0x1e00, v84
	v_add_u32_e32 v86, 0x3c00, v84
	v_add_u32_e32 v87, 0x5a00, v84
	v_lshlrev_b32_e32 v7, 13, v4
	v_add_u32_e32 v7, v7, v6
	v_add_u32_e32 v198, 0x1000, v7
	s_lshl_b32 s2, s17, 13
	s_add_u32 s0, s74, 0x9f20400
	s_addc_u32 s1, s75, 0
	s_add_u32 s0, s0, s2
	s_addc_u32 s1, s1, 0
	s_add_u32 s2, s0, 0x1000
	s_addc_u32 s3, s1, 0
	v_lshlrev_b32_e32 v5, 6, v3
	v_lshl_add_u32 v5, v4, 4, v5
	global_load_dwordx4 v[8:11], v5, s[0:1] offset:0
	global_load_dwordx4 v[12:15], v5, s[0:1] offset:1024
	global_load_dwordx4 v[16:19], v5, s[0:1] offset:2048
	global_load_dwordx4 v[20:23], v5, s[0:1] offset:3072
	global_load_dwordx4 v[24:27], v5, s[2:3] offset:0
	global_load_dwordx4 v[28:31], v5, s[2:3] offset:1024
	global_load_dwordx4 v[32:35], v5, s[2:3] offset:2048
	global_load_dwordx4 v[36:39], v5, s[2:3] offset:3072
	s_lshl_b32 s6, s17, 10
	s_add_u32 s4, s74, 0x9f10400
	s_addc_u32 s5, s75, 0
	s_add_u32 s4, s4, s6
	s_addc_u32 s5, s5, 0
	v_lshlrev_b32_e32 v6, 4, v2
	global_load_dwordx4 v[72:75], v6, s[4:5]
	s_lshl_b32 s6, s17, 12
	s_add_u32 s8, s62, s6
	s_addc_u32 s9, s63, 0
	s_add_u32 s10, s64, s6
	s_addc_u32 s11, s65, 0
	v_lshlrev_b32_e32 v7, 8, v3
	v_lshl_add_u32 v7, v4, 4, v7
	global_load_dword v40, v7, s[8:9] offset:0
	global_load_dword v41, v7, s[8:9] offset:4
	global_load_dword v42, v7, s[8:9] offset:8
	global_load_dword v43, v7, s[8:9] offset:12
	global_load_dword v44, v7, s[8:9] offset:64
	global_load_dword v45, v7, s[8:9] offset:68
	global_load_dword v46, v7, s[8:9] offset:72
	global_load_dword v47, v7, s[8:9] offset:76
	global_load_dword v48, v7, s[8:9] offset:128
	global_load_dword v49, v7, s[8:9] offset:132
	global_load_dword v50, v7, s[8:9] offset:136
	global_load_dword v51, v7, s[8:9] offset:140
	global_load_dword v52, v7, s[8:9] offset:192
	global_load_dword v53, v7, s[8:9] offset:196
	global_load_dword v54, v7, s[8:9] offset:200
	global_load_dword v55, v7, s[8:9] offset:204
	global_load_dword v56, v7, s[10:11] offset:0
	global_load_dword v57, v7, s[10:11] offset:4
	global_load_dword v58, v7, s[10:11] offset:8
	global_load_dword v59, v7, s[10:11] offset:12
	global_load_dword v60, v7, s[10:11] offset:64
	global_load_dword v61, v7, s[10:11] offset:68
	global_load_dword v62, v7, s[10:11] offset:72
	global_load_dword v63, v7, s[10:11] offset:76
	global_load_dword v64, v7, s[10:11] offset:128
	global_load_dword v65, v7, s[10:11] offset:132
	global_load_dword v66, v7, s[10:11] offset:136
	global_load_dword v67, v7, s[10:11] offset:140
	global_load_dword v68, v7, s[10:11] offset:192
	global_load_dword v69, v7, s[10:11] offset:196
	global_load_dword v70, v7, s[10:11] offset:200
	global_load_dword v71, v7, s[10:11] offset:204
	s_lshl_b32 s6, s17, 6
	s_add_u32 s12, s66, s6
	s_addc_u32 s13, s67, 0
	v_lshlrev_b32_e32 v6, 2, v3
	global_load_dword v76, v6, s[12:13]
	s_mul_i32 s0, s18, 0x78000
	s_lshl_b32 s1, s17, 5
	s_add_i32 s0, s0, s1
	s_add_i32 s0, s0, 0xf911430
	s_add_u32 s22, s74, s0
	s_addc_u32 s23, s75, 0
	s_lshl_b32 s0, s17, 14
	s_add_i32 s0, s0, 0xa110000
	s_add_u32 s24, s74, s0
	s_addc_u32 s25, s75, 0
	s_lshl_b32 s0, s18, 17
	s_lshl_b32 s1, s17, 5
	s_add_i32 s0, s0, s1
	s_add_i32 s0, s0, 0xb910000
	s_add_u32 s26, s74, s0
	s_addc_u32 s27, s75, 0
	s_add_u32 s40, s22, 0x0
	s_addc_u32 s41, s23, 0
	s_add_u32 s42, s22, 0x1e000
	s_addc_u32 s43, s23, 0
	s_add_u32 s44, s22, 0x3c000
	s_addc_u32 s45, s23, 0
	s_add_u32 s46, s22, 0x5a000
	s_addc_u32 s47, s23, 0
	global_load_dwordx4 v[120:123], v83, s[40:41]
	global_load_dwordx4 v[124:127], v83, s[42:43]
	global_load_dwordx4 v[128:131], v83, s[44:45]
	global_load_dwordx4 v[132:135], v83, s[46:47]
	global_load_ushort v136, v84, s[40:41]
	global_load_ushort v137, v85, s[40:41]
	global_load_ushort v138, v86, s[40:41]
	global_load_ushort v139, v87, s[40:41]
	global_load_ushort v140, v84, s[42:43]
	global_load_ushort v141, v85, s[42:43]
	global_load_ushort v142, v86, s[42:43]
	global_load_ushort v143, v87, s[42:43]
	global_load_ushort v144, v84, s[44:45]
	global_load_ushort v145, v85, s[44:45]
	global_load_ushort v146, v86, s[44:45]
	global_load_ushort v147, v87, s[44:45]
	global_load_ushort v148, v84, s[46:47]
	global_load_ushort v149, v85, s[46:47]
	global_load_ushort v150, v86, s[46:47]
	global_load_ushort v151, v87, s[46:47]
	global_load_dwordx2 v[152:153], v199, s[24:25] offset:-4096
	global_load_dwordx2 v[154:155], v199, s[24:25]
	global_load_dwordx2 v[156:157], v204, s[24:25] offset:-4096
	global_load_dwordx2 v[158:159], v204, s[24:25]
	s_mov_b32 s19, 0
	s_mov_b32 s20, 0
	s_waitcnt vmcnt(0)
	v_xor_b32_e32 v56, 0x80000000, v56
	v_xor_b32_e32 v57, 0x80000000, v57
	v_xor_b32_e32 v58, 0x80000000, v58
	v_xor_b32_e32 v59, 0x80000000, v59
	v_xor_b32_e32 v60, 0x80000000, v60
	v_xor_b32_e32 v61, 0x80000000, v61
	v_xor_b32_e32 v62, 0x80000000, v62
	v_xor_b32_e32 v63, 0x80000000, v63
	v_xor_b32_e32 v64, 0x80000000, v64
	v_xor_b32_e32 v65, 0x80000000, v65
	v_xor_b32_e32 v66, 0x80000000, v66
	v_xor_b32_e32 v67, 0x80000000, v67
	v_xor_b32_e32 v68, 0x80000000, v68
	v_xor_b32_e32 v69, 0x80000000, v69
	v_xor_b32_e32 v70, 0x80000000, v70
	v_xor_b32_e32 v71, 0x80000000, v71

; DI void s5_bu16(const bf16x8 ub, const bf16x8 (&af)[8], float* buf, int r, int q) {
; #pragma unroll
;     for (int pt = 0; pt < 8; ++pt) { f32x4 d = {0.f, 0.f, 0.f, 0.f}; d = __builtin_amdgcn_mfma_f32_16x16x32_bf16(af[pt], ub, d, 0, 0, 0);
; #pragma unroll
;         for (int j = 0; j < 4; ++j) buf[(16 * pt + 4 * q + j) * 17 + r] = d[j]; }
; DI void s5_pass3_item(const Params& P, int bitem, unsigned char* smem) {
;     ...
; #pragma unroll
;         for (int tt = 0; tt < 16; ++tt) { const float bur = xs[lane * 17 + tt], bui = xs[(64 + lane) * 17 + tt];
;             const float nxr = ab[0] * xr - ab[1] * xi + bur, nxi = ab[0] * xi + ab[1] * xr + bui; xr = nxr; xi = nxi;
;             xs[lane * 17 + tt] = xr; xs[(64 + lane) * 17 + tt] = xi; }
.Ls5n_cdone:
	s_waitcnt lgkmcnt(0)
	s_mov_b64 s[28:29], s[26:27]
	v_mfma_f32_16x16x32_bf16 v[160:163], v[8:11], v[88:91], 0
	v_mfma_f32_16x16x32_bf16 v[164:167], v[12:15], v[88:91], 0
	v_mfma_f32_16x16x32_bf16 v[168:171], v[16:19], v[88:91], 0
	v_mfma_f32_16x16x32_bf16 v[172:175], v[20:23], v[88:91], 0
	v_mfma_f32_16x16x32_bf16 v[176:179], v[24:27], v[88:91], 0
	v_mfma_f32_16x16x32_bf16 v[180:183], v[28:31], v[88:91], 0
	v_mfma_f32_16x16x32_bf16 v[184:187], v[32:35], v[88:91], 0
	v_mfma_f32_16x16x32_bf16 v[188:191], v[36:39], v[88:91], 0
	s_nop 1
	ds_write_b128 v77, v[160:163] offset:0
	ds_write_b128 v77, v[164:167] offset:64
	ds_write_b128 v77, v[168:171] offset:128
	ds_write_b128 v77, v[172:175] offset:192
	ds_write_b128 v77, v[176:179] offset:256
	ds_write_b128 v77, v[180:183] offset:320
	ds_write_b128 v77, v[184:187] offset:384
	ds_write_b128 v77, v[188:191] offset:448
	ds_read_addtid_b32 v208 offset:0
	ds_read_addtid_b32 v224 offset:256
	ds_read_addtid_b32 v209 offset:528
	ds_read_addtid_b32 v225 offset:784
	ds_read_addtid_b32 v210 offset:1056
	ds_read_addtid_b32 v226 offset:1312
	ds_read_addtid_b32 v211 offset:1584
	ds_read_addtid_b32 v227 offset:1840
	ds_read_addtid_b32 v212 offset:2112
	ds_read_addtid_b32 v228 offset:2368
	ds_read_addtid_b32 v213 offset:2640
	ds_read_addtid_b32 v229 offset:2896
	ds_read_addtid_b32 v214 offset:3168
	ds_read_addtid_b32 v230 offset:3424
	ds_read_addtid_b32 v215 offset:3696
	ds_read_addtid_b32 v231 offset:3952
	ds_read_addtid_b32 v216 offset:4224
	ds_read_addtid_b32 v232 offset:4480
	ds_read_addtid_b32 v217 offset:4752
	ds_read_addtid_b32 v233 offset:5008
	ds_read_addtid_b32 v218 offset:5280
	ds_read_addtid_b32 v234 offset:5536
	ds_read_addtid_b32 v219 offset:5808
	ds_read_addtid_b32 v235 offset:6064
	ds_read_addtid_b32 v220 offset:6336
	ds_read_addtid_b32 v236 offset:6592
	ds_read_addtid_b32 v221 offset:6864
	ds_read_addtid_b32 v237 offset:7120
	ds_read_addtid_b32 v222 offset:7392
	ds_read_addtid_b32 v238 offset:7648
	ds_read_addtid_b32 v223 offset:7920
	ds_read_addtid_b32 v239 offset:8176
	s_waitcnt lgkmcnt(15)
	v_mul_f32_e32 v194, v73, v193
	v_mul_f32_e32 v195, v73, v192
	v_fma_f32 v194, v72, v192, -v194
	v_fma_f32 v195, v72, v193, v195
	v_add_f32_e32 v208, v194, v208
	v_add_f32_e32 v224, v195, v224
	ds_write_addtid_b32 v208 offset:0
	ds_write_addtid_b32 v224 offset:256
	s_waitcnt lgkmcnt(15)
	v_mul_f32_e32 v194, v73, v224
	v_mul_f32_e32 v195, v73, v208
	v_fma_f32 v194, v72, v208, -v194
	v_fma_f32 v195, v72, v224, v195
	v_add_f32_e32 v209, v194, v209
	v_add_f32_e32 v225, v195, v225
	ds_write_addtid_b32 v209 offset:528
	ds_write_addtid_b32 v225 offset:784
	s_waitcnt lgkmcnt(15)
	v_mul_f32_e32 v194, v73, v225
	v_mul_f32_e32 v195, v73, v209
	v_fma_f32 v194, v72, v209, -v194
	v_fma_f32 v195, v72, v225, v195
	v_add_f32_e32 v210, v194, v210
	v_add_f32_e32 v226, v195, v226
	ds_write_addtid_b32 v210 offset:1056
	ds_write_addtid_b32 v226 offset:1312
	s_waitcnt lgkmcnt(15)
	v_mul_f32_e32 v194, v73, v226
	v_mul_f32_e32 v195, v73, v210
	v_fma_f32 v194, v72, v210, -v194
	v_fma_f32 v195, v72, v226, v195
	v_add_f32_e32 v211, v194, v211
	v_add_f32_e32 v227, v195, v227
	ds_write_addtid_b32 v211 offset:1584
	ds_write_addtid_b32 v227 offset:1840
	s_waitcnt lgkmcnt(15)
	v_mul_f32_e32 v194, v73, v227
	v_mul_f32_e32 v195, v73, v211
	v_fma_f32 v194, v72, v211, -v194
	v_fma_f32 v195, v72, v227, v195
	v_add_f32_e32 v212, v194, v212
	v_add_f32_e32 v228, v195, v228
	ds_write_addtid_b32 v212 offset:2112
	ds_write_addtid_b32 v228 offset:2368
	s_waitcnt lgkmcnt(15)
	v_mul_f32_e32 v194, v73, v228
	v_mul_f32_e32 v195, v73, v212
	v_fma_f32 v194, v72, v212, -v194
	v_fma_f32 v195, v72, v228, v195
	v_add_f32_e32 v213, v194, v213
	v_add_f32_e32 v229, v195, v229
	ds_write_addtid_b32 v213 offset:2640
	ds_write_addtid_b32 v229 offset:2896
	s_waitcnt lgkmcnt(15)
	v_mul_f32_e32 v194, v73, v229
	v_mul_f32_e32 v195, v73, v213
	v_fma_f32 v194, v72, v213, -v194
	v_fma_f32 v195, v72, v229, v195
	v_add_f32_e32 v214, v194, v214
	v_add_f32_e32 v230, v195, v230
	ds_write_addtid_b32 v214 offset:3168
	ds_write_addtid_b32 v230 offset:3424
	s_waitcnt lgkmcnt(15)
	v_mul_f32_e32 v194, v73, v230
	v_mul_f32_e32 v195, v73, v214
	v_fma_f32 v194, v72, v214, -v194
	v_fma_f32 v195, v72, v230, v195
	v_add_f32_e32 v215, v194, v215
	v_add_f32_e32 v231, v195, v231
	ds_write_addtid_b32 v215 offset:3696
	ds_write_addtid_b32 v231 offset:3952
	s_waitcnt lgkmcnt(15)
	v_mul_f32_e32 v194, v73, v231
	v_mul_f32_e32 v195, v73, v215
	v_fma_f32 v194, v72, v215, -v194
	v_fma_f32 v195, v72, v231, v195
	v_add_f32_e32 v216, v194, v216
	v_add_f32_e32 v232, v195, v232
	ds_write_addtid_b32 v216 offset:4224
	ds_write_addtid_b32 v232 offset:4480
	s_waitcnt lgkmcnt(15)
	v_mul_f32_e32 v194, v73, v232
	v_mul_f32_e32 v195, v73, v216
	v_fma_f32 v194, v72, v216, -v194
	v_fma_f32 v195, v72, v232, v195
	v_add_f32_e32 v217, v194, v217
	v_add_f32_e32 v233, v195, v233
	ds_write_addtid_b32 v217 offset:4752
	ds_write_addtid_b32 v233 offset:5008
	s_waitcnt lgkmcnt(15)
	v_mul_f32_e32 v194, v73, v233
	v_mul_f32_e32 v195, v73, v217
	v_fma_f32 v194, v72, v217, -v194
	v_fma_f32 v195, v72, v233, v195
	v_add_f32_e32 v218, v194, v218
	v_add_f32_e32 v234, v195, v234
	ds_write_addtid_b32 v218 offset:5280
	ds_write_addtid_b32 v234 offset:5536
	s_waitcnt lgkmcnt(15)
	v_mul_f32_e32 v194, v73, v234
	v_mul_f32_e32 v195, v73, v218
	v_fma_f32 v194, v72, v218, -v194
	v_fma_f32 v195, v72, v234, v195
	v_add_f32_e32 v219, v194, v219
	v_add_f32_e32 v235, v195, v235
	ds_write_addtid_b32 v219 offset:5808
	ds_write_addtid_b32 v235 offset:6064
	s_waitcnt lgkmcnt(15)
; DI unsigned pk2(float a, float b) { f32x2_t v = {a, b}; return __builtin_bit_cast(unsigned, __builtin_convertvector(v, bf16x2_t)); }
; DI float gelu_tanh(float v) { const float z = 0.7978845608028654f * (v + 0.044715f * v * v * v); const float th = 1.0f - 2.0f * __builtin_amdgcn_rcpf(__builtin_amdgcn_exp2f(2.8853900817779268f * z) + 1.0f); return 0.5f * v * (1.0f + th); }
; DI void s5_pass3_item(const Params& P, int bitem, unsigned char* smem) {
;     ...
; #pragma unroll
;         for (int tt = 0; tt < 16; ++tt) { const float bur = xs[lane * 17 + tt], bui = xs[(64 + lane) * 17 + tt];
;             const float nxr = ab[0] * xr - ab[1] * xi + bur, nxi = ab[0] * xi + ab[1] * xr + bui; xr = nxr; xi = nxi;
;             xs[lane * 17 + tt] = xr; xs[(64 + lane) * 17 + tt] = xi; }
;         asm volatile("s_waitcnt lgkmcnt(0)" ::: "memory");
;         f32x4 ya[4];
; #pragma unroll
;         for (int j = 0; j < 4; ++j) ya[j] = (f32x4){0.f, 0.f, 0.f, 0.f};
; #pragma unroll
;         for (int i = 0; i < 32; ++i) { const float a = xs[(4 * i + q) * 17 + r]; ya[i & 3] = __builtin_amdgcn_mfma_f32_16x16x4f32(a, cB[i], ya[i & 3], 0, 0, 0); }
;         const f32x4 y = (ya[0] + ya[1]) + (ya[2] + ya[3]);
; #pragma unroll
;         for (int j = 0; j < 4; ++j) { const int tl = sub * 16 + 4 * q + j; const float v = y[j] + dsk * uv[j];
;             HG[(size_t)(b * TT + ch * 64 + tl) * 1024 + grp * 16 + r] = (bf16_t)(pk2(gelu_tanh(v), 0.f) & 0xffffu); }
	v_mul_f32_e32 v194, v73, v235
	v_mul_f32_e32 v195, v73, v219
	v_fma_f32 v194, v72, v219, -v194
	v_fma_f32 v195, v72, v235, v195
	v_add_f32_e32 v220, v194, v220
	v_add_f32_e32 v236, v195, v236
	ds_write_addtid_b32 v220 offset:6336
	ds_write_addtid_b32 v236 offset:6592
	s_waitcnt lgkmcnt(15)
	v_mul_f32_e32 v194, v73, v236
	v_mul_f32_e32 v195, v73, v220
	v_fma_f32 v194, v72, v220, -v194
	v_fma_f32 v195, v72, v236, v195
	v_add_f32_e32 v221, v194, v221
	v_add_f32_e32 v237, v195, v237
	ds_write_addtid_b32 v221 offset:6864
	ds_write_addtid_b32 v237 offset:7120
	s_waitcnt lgkmcnt(15)
	v_mul_f32_e32 v194, v73, v237
	v_mul_f32_e32 v195, v73, v221
	v_fma_f32 v194, v72, v221, -v194
	v_fma_f32 v195, v72, v237, v195
	v_add_f32_e32 v222, v194, v222
	v_add_f32_e32 v238, v195, v238
	ds_write_addtid_b32 v222 offset:7392
	ds_write_addtid_b32 v238 offset:7648
	s_waitcnt lgkmcnt(15)
	v_mul_f32_e32 v194, v73, v238
	v_mul_f32_e32 v195, v73, v222
	v_fma_f32 v194, v72, v222, -v194
	v_fma_f32 v195, v72, v238, v195
	v_add_f32_e32 v223, v194, v223
	v_add_f32_e32 v239, v195, v239
	ds_write_addtid_b32 v223 offset:7920
	ds_write_addtid_b32 v239 offset:8176
	v_mov_b32_e32 v192, v223
	v_mov_b32_e32 v193, v239
	ds_read_b128 v[160:163], v77 offset:0
	ds_read_b128 v[164:167], v77 offset:64
	ds_read_b128 v[168:171], v77 offset:128
	ds_read_b128 v[172:175], v77 offset:192
	ds_read_b128 v[176:179], v77 offset:256
	ds_read_b128 v[180:183], v77 offset:320
	ds_read_b128 v[184:187], v77 offset:384
	ds_read_b128 v[188:191], v77 offset:448
	s_waitcnt lgkmcnt(7)
	v_mfma_f32_16x16x4_f32 v[200:203], v160, v40, 0
	s_waitcnt lgkmcnt(7)
	v_mfma_f32_16x16x4_f32 v[240:243], v161, v41, 0
	s_waitcnt lgkmcnt(7)
	v_mfma_f32_16x16x4_f32 v[200:203], v162, v42, v[200:203]
	s_waitcnt lgkmcnt(7)
	v_mfma_f32_16x16x4_f32 v[240:243], v163, v43, v[240:243]
	s_waitcnt lgkmcnt(6)
	v_mfma_f32_16x16x4_f32 v[200:203], v164, v44, v[200:203]
	s_waitcnt lgkmcnt(6)
	v_mfma_f32_16x16x4_f32 v[240:243], v165, v45, v[240:243]
	s_waitcnt lgkmcnt(6)
	v_mfma_f32_16x16x4_f32 v[200:203], v166, v46, v[200:203]
	s_waitcnt lgkmcnt(6)
	v_mfma_f32_16x16x4_f32 v[240:243], v167, v47, v[240:243]
	s_waitcnt lgkmcnt(5)
	v_mfma_f32_16x16x4_f32 v[200:203], v168, v48, v[200:203]
	s_waitcnt lgkmcnt(5)
	v_mfma_f32_16x16x4_f32 v[240:243], v169, v49, v[240:243]
	s_waitcnt lgkmcnt(5)
	v_mfma_f32_16x16x4_f32 v[200:203], v170, v50, v[200:203]
	s_waitcnt lgkmcnt(5)
	v_mfma_f32_16x16x4_f32 v[240:243], v171, v51, v[240:243]
	s_waitcnt lgkmcnt(4)
	v_mfma_f32_16x16x4_f32 v[200:203], v172, v52, v[200:203]
	s_waitcnt lgkmcnt(4)
	v_mfma_f32_16x16x4_f32 v[240:243], v173, v53, v[240:243]
	s_waitcnt lgkmcnt(4)
	v_mfma_f32_16x16x4_f32 v[200:203], v174, v54, v[200:203]
	s_waitcnt lgkmcnt(4)
	v_mfma_f32_16x16x4_f32 v[240:243], v175, v55, v[240:243]
	s_waitcnt lgkmcnt(3)
	v_mfma_f32_16x16x4_f32 v[200:203], v176, v56, v[200:203]
	s_waitcnt lgkmcnt(3)
	v_mfma_f32_16x16x4_f32 v[240:243], v177, v57, v[240:243]
	s_waitcnt lgkmcnt(3)
	v_mfma_f32_16x16x4_f32 v[200:203], v178, v58, v[200:203]
	s_waitcnt lgkmcnt(3)
	v_mfma_f32_16x16x4_f32 v[240:243], v179, v59, v[240:243]
	s_waitcnt lgkmcnt(2)
	v_mfma_f32_16x16x4_f32 v[200:203], v180, v60, v[200:203]
	s_waitcnt lgkmcnt(2)
	v_mfma_f32_16x16x4_f32 v[240:243], v181, v61, v[240:243]
	s_waitcnt lgkmcnt(2)
	v_mfma_f32_16x16x4_f32 v[200:203], v182, v62, v[200:203]
	s_waitcnt lgkmcnt(2)
	v_mfma_f32_16x16x4_f32 v[240:243], v183, v63, v[240:243]
	s_waitcnt lgkmcnt(1)
	v_mfma_f32_16x16x4_f32 v[200:203], v184, v64, v[200:203]
	s_waitcnt lgkmcnt(1)
	v_mfma_f32_16x16x4_f32 v[240:243], v185, v65, v[240:243]
	s_waitcnt lgkmcnt(1)
	v_mfma_f32_16x16x4_f32 v[200:203], v186, v66, v[200:203]
	s_waitcnt lgkmcnt(1)
	v_mfma_f32_16x16x4_f32 v[240:243], v187, v67, v[240:243]
	s_waitcnt lgkmcnt(0)
	v_mfma_f32_16x16x4_f32 v[200:203], v188, v68, v[200:203]
	s_waitcnt lgkmcnt(0)
	v_mfma_f32_16x16x4_f32 v[240:243], v189, v69, v[240:243]
	s_waitcnt lgkmcnt(0)
	v_mfma_f32_16x16x4_f32 v[200:203], v190, v70, v[200:203]
	s_waitcnt lgkmcnt(0)
	v_mfma_f32_16x16x4_f32 v[240:243], v191, v71, v[240:243]
	s_nop 9
	v_add_f32_e32 v1, v200, v240
	v_add_f32_e32 v2, v201, v241
	v_add_f32_e32 v3, v202, v242
	v_add_f32_e32 v4, v203, v243
	v_fmac_f32_e32 v1, v76, v104
	v_fmac_f32_e32 v2, v76, v105
	v_fmac_f32_e32 v3, v76, v106
	v_fmac_f32_e32 v4, v76, v107
	v_mul_f32_e32 v5, 0x3d372713, v1
	v_mul_f32_e32 v6, 0x3d372713, v2
	v_mul_f32_e32 v7, 0x3d372713, v3
	v_mul_f32_e32 v246, 0x3d372713, v4
	v_mul_f32_e32 v5, v1, v5
	v_mul_f32_e32 v6, v2, v6
	v_mul_f32_e32 v7, v3, v7
	v_mul_f32_e32 v246, v4, v246
	v_mul_f32_e32 v194, 0.5, v1
	v_mul_f32_e32 v195, 0.5, v2
	v_mul_f32_e32 v196, 0.5, v3
	v_mul_f32_e32 v197, 0.5, v4
	v_fma_f32 v1, v1, v5, v1
	v_fma_f32 v2, v2, v6, v2
	v_fma_f32 v3, v3, v7, v3
	v_fma_f32 v4, v4, v246, v4
	v_mul_f32_e32 v1, 0x3f4c422a, v1
	v_mul_f32_e32 v2, 0x3f4c422a, v2
	v_mul_f32_e32 v3, 0x3f4c422a, v3
	v_mul_f32_e32 v4, 0x3f4c422a, v4
	v_mul_f32_e32 v1, 0x4038aa3b, v1
	v_mul_f32_e32 v2, 0x4038aa3b, v2
	v_mul_f32_e32 v3, 0x4038aa3b, v3
	v_mul_f32_e32 v4, 0x4038aa3b, v4
	v_exp_f32_e32 v1, v1
	v_exp_f32_e32 v2, v2
	v_exp_f32_e32 v3, v3
	v_exp_f32_e32 v4, v4
	v_add_f32_e32 v1, 1.0, v1
	v_add_f32_e32 v2, 1.0, v2
	v_add_f32_e32 v3, 1.0, v3
	v_add_f32_e32 v4, 1.0, v4
	v_rcp_f32_e32 v1, v1
	v_rcp_f32_e32 v2, v2
	v_rcp_f32_e32 v3, v3
	v_rcp_f32_e32 v4, v4
	v_fma_f32 v1, v1, -2.0, 1.0
	v_fma_f32 v2, v2, -2.0, 1.0
	v_fma_f32 v3, v3, -2.0, 1.0
	v_fma_f32 v4, v4, -2.0, 1.0
	v_add_f32_e32 v1, 1.0, v1
	v_add_f32_e32 v2, 1.0, v2
	v_add_f32_e32 v3, 1.0, v3
	v_add_f32_e32 v4, 1.0, v4
	v_mul_f32_e32 v1, v194, v1
	v_mul_f32_e32 v2, v195, v2
	v_mul_f32_e32 v3, v196, v3
; DI unsigned pk2(float a, float b) { f32x2_t v = {a, b}; return __builtin_bit_cast(unsigned, __builtin_convertvector(v, bf16x2_t)); }
; DI float bf2f(unsigned x) { return __uint_as_float(x << 16); }
; DI float gelu_tanh(float v) { const float z = 0.7978845608028654f * (v + 0.044715f * v * v * v); const float th = 1.0f - 2.0f * __builtin_amdgcn_rcpf(__builtin_amdgcn_exp2f(2.8853900817779268f * z) + 1.0f); return 0.5f * v * (1.0f + th); }
; DI void s5_pass3_item(const Params& P, int bitem, unsigned char* smem) {
;     ...
;     for (int sub = 0; sub < 4; ++sub) {
;         s5_bu16(ubs[sub], af, xs, r, q);
;         float uv[4];
; #pragma unroll
;         for (int j = 0; j < 4; ++j) uv[j] = bf2f(uvs[sub][j]);
;         asm volatile("s_waitcnt lgkmcnt(0)" ::: "memory");
; #pragma unroll
;         for (int tt = 0; tt < 16; ++tt) { const float bur = xs[lane * 17 + tt], bui = xs[(64 + lane) * 17 + tt];
;             const float nxr = ab[0] * xr - ab[1] * xi + bur, nxi = ab[0] * xi + ab[1] * xr + bui; xr = nxr; xi = nxi;
;             xs[lane * 17 + tt] = xr; xs[(64 + lane) * 17 + tt] = xi; }
;         asm volatile("s_waitcnt lgkmcnt(0)" ::: "memory");
;         f32x4 ya[4];
; #pragma unroll
;         for (int j = 0; j < 4; ++j) ya[j] = (f32x4){0.f, 0.f, 0.f, 0.f};
; #pragma unroll
;         for (int i = 0; i < 32; ++i) { const float a = xs[(4 * i + q) * 17 + r]; ya[i & 3] = __builtin_amdgcn_mfma_f32_16x16x4f32(a, cB[i], ya[i & 3], 0, 0, 0); }
;         const f32x4 y = (ya[0] + ya[1]) + (ya[2] + ya[3]);
; #pragma unroll
;         for (int j = 0; j < 4; ++j) { const int tl = sub * 16 + 4 * q + j; const float v = y[j] + dsk * uv[j];
;             HG[(size_t)(b * TT + ch * 64 + tl) * 1024 + grp * 16 + r] = (bf16_t)(pk2(gelu_tanh(v), 0.f) & 0xffffu); }
	v_mul_f32_e32 v4, v197, v4
	v_cvt_pk_bf16_f32 v1, v1, v1
	v_cvt_pk_bf16_f32 v2, v2, v2
	v_cvt_pk_bf16_f32 v3, v3, v3
	v_cvt_pk_bf16_f32 v4, v4, v4
	global_store_short v198, v1, s[28:29] offset:-4096
	global_store_short v198, v2, s[28:29] offset:-2048
	global_store_short v198, v3, s[28:29] offset:0
	global_store_short v198, v4, s[28:29] offset:2048
	s_add_u32 s28, s28, 0x8000
	s_addc_u32 s29, s29, 0
	v_mfma_f32_16x16x32_bf16 v[160:163], v[8:11], v[92:95], 0
	v_mfma_f32_16x16x32_bf16 v[164:167], v[12:15], v[92:95], 0
	v_mfma_f32_16x16x32_bf16 v[168:171], v[16:19], v[92:95], 0
	v_mfma_f32_16x16x32_bf16 v[172:175], v[20:23], v[92:95], 0
	v_mfma_f32_16x16x32_bf16 v[176:179], v[24:27], v[92:95], 0
	v_mfma_f32_16x16x32_bf16 v[180:183], v[28:31], v[92:95], 0
	v_mfma_f32_16x16x32_bf16 v[184:187], v[32:35], v[92:95], 0
	v_mfma_f32_16x16x32_bf16 v[188:191], v[36:39], v[92:95], 0
	s_nop 1
	ds_write_b128 v77, v[160:163] offset:0
	ds_write_b128 v77, v[164:167] offset:64
	ds_write_b128 v77, v[168:171] offset:128
	ds_write_b128 v77, v[172:175] offset:192
	ds_write_b128 v77, v[176:179] offset:256
	ds_write_b128 v77, v[180:183] offset:320
	ds_write_b128 v77, v[184:187] offset:384
	ds_write_b128 v77, v[188:191] offset:448
	ds_read_addtid_b32 v208 offset:0
	ds_read_addtid_b32 v224 offset:256
	ds_read_addtid_b32 v209 offset:528
	ds_read_addtid_b32 v225 offset:784
	ds_read_addtid_b32 v210 offset:1056
	ds_read_addtid_b32 v226 offset:1312
	ds_read_addtid_b32 v211 offset:1584
	ds_read_addtid_b32 v227 offset:1840
	ds_read_addtid_b32 v212 offset:2112
	ds_read_addtid_b32 v228 offset:2368
	ds_read_addtid_b32 v213 offset:2640
	ds_read_addtid_b32 v229 offset:2896
	ds_read_addtid_b32 v214 offset:3168
	ds_read_addtid_b32 v230 offset:3424
	ds_read_addtid_b32 v215 offset:3696
	ds_read_addtid_b32 v231 offset:3952
	ds_read_addtid_b32 v216 offset:4224
	ds_read_addtid_b32 v232 offset:4480
	ds_read_addtid_b32 v217 offset:4752
	ds_read_addtid_b32 v233 offset:5008
	ds_read_addtid_b32 v218 offset:5280
	ds_read_addtid_b32 v234 offset:5536
	ds_read_addtid_b32 v219 offset:5808
	ds_read_addtid_b32 v235 offset:6064
	ds_read_addtid_b32 v220 offset:6336
	ds_read_addtid_b32 v236 offset:6592
	ds_read_addtid_b32 v221 offset:6864
	ds_read_addtid_b32 v237 offset:7120
	ds_read_addtid_b32 v222 offset:7392
	ds_read_addtid_b32 v238 offset:7648
	ds_read_addtid_b32 v223 offset:7920
	ds_read_addtid_b32 v239 offset:8176
	s_waitcnt lgkmcnt(15)
	v_mul_f32_e32 v194, v73, v193
	v_mul_f32_e32 v195, v73, v192
	v_fma_f32 v194, v72, v192, -v194
	v_fma_f32 v195, v72, v193, v195
	v_add_f32_e32 v208, v194, v208
	v_add_f32_e32 v224, v195, v224
	ds_write_addtid_b32 v208 offset:0
	ds_write_addtid_b32 v224 offset:256
	s_waitcnt lgkmcnt(15)
	v_mul_f32_e32 v194, v73, v224
	v_mul_f32_e32 v195, v73, v208
	v_fma_f32 v194, v72, v208, -v194
	v_fma_f32 v195, v72, v224, v195
	v_add_f32_e32 v209, v194, v209
	v_add_f32_e32 v225, v195, v225
	ds_write_addtid_b32 v209 offset:528
	ds_write_addtid_b32 v225 offset:784
	s_waitcnt lgkmcnt(15)
	v_mul_f32_e32 v194, v73, v225
	v_mul_f32_e32 v195, v73, v209
	v_fma_f32 v194, v72, v209, -v194
	v_fma_f32 v195, v72, v225, v195
	v_add_f32_e32 v210, v194, v210
	v_add_f32_e32 v226, v195, v226
	ds_write_addtid_b32 v210 offset:1056
	ds_write_addtid_b32 v226 offset:1312
	s_waitcnt lgkmcnt(15)
	v_mul_f32_e32 v194, v73, v226
	v_mul_f32_e32 v195, v73, v210
	v_fma_f32 v194, v72, v210, -v194
	v_fma_f32 v195, v72, v226, v195
	v_add_f32_e32 v211, v194, v211
	v_add_f32_e32 v227, v195, v227
	ds_write_addtid_b32 v211 offset:1584
	ds_write_addtid_b32 v227 offset:1840
	s_waitcnt lgkmcnt(15)
	v_mul_f32_e32 v194, v73, v227
	v_mul_f32_e32 v195, v73, v211
	v_fma_f32 v194, v72, v211, -v194
	v_fma_f32 v195, v72, v227, v195
	v_add_f32_e32 v212, v194, v212
	v_add_f32_e32 v228, v195, v228
	ds_write_addtid_b32 v212 offset:2112
	ds_write_addtid_b32 v228 offset:2368
	s_waitcnt lgkmcnt(15)
	v_mul_f32_e32 v194, v73, v228
	v_mul_f32_e32 v195, v73, v212
	v_fma_f32 v194, v72, v212, -v194
	v_fma_f32 v195, v72, v228, v195
	v_add_f32_e32 v213, v194, v213
	v_add_f32_e32 v229, v195, v229
	ds_write_addtid_b32 v213 offset:2640
	ds_write_addtid_b32 v229 offset:2896
	s_waitcnt lgkmcnt(15)
	v_mul_f32_e32 v194, v73, v229
	v_mul_f32_e32 v195, v73, v213
	v_fma_f32 v194, v72, v213, -v194
	v_fma_f32 v195, v72, v229, v195
	v_add_f32_e32 v214, v194, v214
	v_add_f32_e32 v230, v195, v230
	ds_write_addtid_b32 v214 offset:3168
	ds_write_addtid_b32 v230 offset:3424
	s_waitcnt lgkmcnt(15)
	v_mul_f32_e32 v194, v73, v230
	v_mul_f32_e32 v195, v73, v214
	v_fma_f32 v194, v72, v214, -v194
	v_fma_f32 v195, v72, v230, v195
	v_add_f32_e32 v215, v194, v215
	v_add_f32_e32 v231, v195, v231
	ds_write_addtid_b32 v215 offset:3696
	ds_write_addtid_b32 v231 offset:3952
	s_waitcnt lgkmcnt(15)
	v_mul_f32_e32 v194, v73, v231
	v_mul_f32_e32 v195, v73, v215
	v_fma_f32 v194, v72, v215, -v194
	v_fma_f32 v195, v72, v231, v195
	v_add_f32_e32 v216, v194, v216
	v_add_f32_e32 v232, v195, v232
	ds_write_addtid_b32 v216 offset:4224
	ds_write_addtid_b32 v232 offset:4480
	s_waitcnt lgkmcnt(15)
	v_mul_f32_e32 v194, v73, v232
	v_mul_f32_e32 v195, v73, v216
	v_fma_f32 v194, v72, v216, -v194
	v_fma_f32 v195, v72, v232, v195
	v_add_f32_e32 v217, v194, v217
	v_add_f32_e32 v233, v195, v233
	ds_write_addtid_b32 v217 offset:4752
	ds_write_addtid_b32 v233 offset:5008
	s_waitcnt lgkmcnt(15)
	v_mul_f32_e32 v194, v73, v233
	v_mul_f32_e32 v195, v73, v217
	v_fma_f32 v194, v72, v217, -v194
	v_fma_f32 v195, v72, v233, v195
	v_add_f32_e32 v218, v194, v218
	v_add_f32_e32 v234, v195, v234
	ds_write_addtid_b32 v218 offset:5280
	ds_write_addtid_b32 v234 offset:5536
	s_waitcnt lgkmcnt(15)
; DI void s5_pass3_item(const Params& P, int bitem, unsigned char* smem) {
;     ...
; #pragma unroll
;         for (int tt = 0; tt < 16; ++tt) { const float bur = xs[lane * 17 + tt], bui = xs[(64 + lane) * 17 + tt];
;             const float nxr = ab[0] * xr - ab[1] * xi + bur, nxi = ab[0] * xi + ab[1] * xr + bui; xr = nxr; xi = nxi;
;             xs[lane * 17 + tt] = xr; xs[(64 + lane) * 17 + tt] = xi; }
;         asm volatile("s_waitcnt lgkmcnt(0)" ::: "memory");
;         f32x4 ya[4];
; #pragma unroll
;         for (int j = 0; j < 4; ++j) ya[j] = (f32x4){0.f, 0.f, 0.f, 0.f};
; #pragma unroll
;         for (int i = 0; i < 32; ++i) { const float a = xs[(4 * i + q) * 17 + r]; ya[i & 3] = __builtin_amdgcn_mfma_f32_16x16x4f32(a, cB[i], ya[i & 3], 0, 0, 0); }
;         const f32x4 y = (ya[0] + ya[1]) + (ya[2] + ya[3]);
	v_mul_f32_e32 v194, v73, v234
	v_mul_f32_e32 v195, v73, v218
	v_fma_f32 v194, v72, v218, -v194
	v_fma_f32 v195, v72, v234, v195
	v_add_f32_e32 v219, v194, v219
	v_add_f32_e32 v235, v195, v235
	ds_write_addtid_b32 v219 offset:5808
	ds_write_addtid_b32 v235 offset:6064
	s_waitcnt lgkmcnt(15)
	v_mul_f32_e32 v194, v73, v235
	v_mul_f32_e32 v195, v73, v219
	v_fma_f32 v194, v72, v219, -v194
	v_fma_f32 v195, v72, v235, v195
	v_add_f32_e32 v220, v194, v220
	v_add_f32_e32 v236, v195, v236
	ds_write_addtid_b32 v220 offset:6336
	ds_write_addtid_b32 v236 offset:6592
	s_waitcnt lgkmcnt(15)
	v_mul_f32_e32 v194, v73, v236
	v_mul_f32_e32 v195, v73, v220
	v_fma_f32 v194, v72, v220, -v194
	v_fma_f32 v195, v72, v236, v195
	v_add_f32_e32 v221, v194, v221
	v_add_f32_e32 v237, v195, v237
	ds_write_addtid_b32 v221 offset:6864
	ds_write_addtid_b32 v237 offset:7120
	s_waitcnt lgkmcnt(15)
	v_mul_f32_e32 v194, v73, v237
	v_mul_f32_e32 v195, v73, v221
	v_fma_f32 v194, v72, v221, -v194
	v_fma_f32 v195, v72, v237, v195
	v_add_f32_e32 v222, v194, v222
	v_add_f32_e32 v238, v195, v238
	ds_write_addtid_b32 v222 offset:7392
	ds_write_addtid_b32 v238 offset:7648
	s_waitcnt lgkmcnt(15)
	v_mul_f32_e32 v194, v73, v238
	v_mul_f32_e32 v195, v73, v222
	v_fma_f32 v194, v72, v222, -v194
	v_fma_f32 v195, v72, v238, v195
	v_add_f32_e32 v223, v194, v223
	v_add_f32_e32 v239, v195, v239
	ds_write_addtid_b32 v223 offset:7920
	ds_write_addtid_b32 v239 offset:8176
	v_mov_b32_e32 v192, v223
	v_mov_b32_e32 v193, v239
	ds_read_b128 v[160:163], v77 offset:0
	ds_read_b128 v[164:167], v77 offset:64
	ds_read_b128 v[168:171], v77 offset:128
	ds_read_b128 v[172:175], v77 offset:192
	ds_read_b128 v[176:179], v77 offset:256
	ds_read_b128 v[180:183], v77 offset:320
	ds_read_b128 v[184:187], v77 offset:384
	ds_read_b128 v[188:191], v77 offset:448
	s_waitcnt lgkmcnt(7)
	v_mfma_f32_16x16x4_f32 v[200:203], v160, v40, 0
	s_waitcnt lgkmcnt(7)
	v_mfma_f32_16x16x4_f32 v[240:243], v161, v41, 0
	s_waitcnt lgkmcnt(7)
	v_mfma_f32_16x16x4_f32 v[200:203], v162, v42, v[200:203]
	s_waitcnt lgkmcnt(7)
	v_mfma_f32_16x16x4_f32 v[240:243], v163, v43, v[240:243]
	s_waitcnt lgkmcnt(6)
	v_mfma_f32_16x16x4_f32 v[200:203], v164, v44, v[200:203]
	s_waitcnt lgkmcnt(6)
	v_mfma_f32_16x16x4_f32 v[240:243], v165, v45, v[240:243]
	s_waitcnt lgkmcnt(6)
	v_mfma_f32_16x16x4_f32 v[200:203], v166, v46, v[200:203]
	s_waitcnt lgkmcnt(6)
	v_mfma_f32_16x16x4_f32 v[240:243], v167, v47, v[240:243]
	s_waitcnt lgkmcnt(5)
	v_mfma_f32_16x16x4_f32 v[200:203], v168, v48, v[200:203]
	s_waitcnt lgkmcnt(5)
	v_mfma_f32_16x16x4_f32 v[240:243], v169, v49, v[240:243]
	s_waitcnt lgkmcnt(5)
	v_mfma_f32_16x16x4_f32 v[200:203], v170, v50, v[200:203]
	s_waitcnt lgkmcnt(5)
	v_mfma_f32_16x16x4_f32 v[240:243], v171, v51, v[240:243]
	s_waitcnt lgkmcnt(4)
	v_mfma_f32_16x16x4_f32 v[200:203], v172, v52, v[200:203]
	s_waitcnt lgkmcnt(4)
	v_mfma_f32_16x16x4_f32 v[240:243], v173, v53, v[240:243]
	s_waitcnt lgkmcnt(4)
	v_mfma_f32_16x16x4_f32 v[200:203], v174, v54, v[200:203]
	s_waitcnt lgkmcnt(4)
	v_mfma_f32_16x16x4_f32 v[240:243], v175, v55, v[240:243]
	s_waitcnt lgkmcnt(3)
	v_mfma_f32_16x16x4_f32 v[200:203], v176, v56, v[200:203]
	s_waitcnt lgkmcnt(3)
	v_mfma_f32_16x16x4_f32 v[240:243], v177, v57, v[240:243]
	s_waitcnt lgkmcnt(3)
	v_mfma_f32_16x16x4_f32 v[200:203], v178, v58, v[200:203]
	s_waitcnt lgkmcnt(3)
	v_mfma_f32_16x16x4_f32 v[240:243], v179, v59, v[240:243]
	s_waitcnt lgkmcnt(2)
	v_mfma_f32_16x16x4_f32 v[200:203], v180, v60, v[200:203]
	s_waitcnt lgkmcnt(2)
	v_mfma_f32_16x16x4_f32 v[240:243], v181, v61, v[240:243]
	s_waitcnt lgkmcnt(2)
	v_mfma_f32_16x16x4_f32 v[200:203], v182, v62, v[200:203]
	s_waitcnt lgkmcnt(2)
	v_mfma_f32_16x16x4_f32 v[240:243], v183, v63, v[240:243]
	s_waitcnt lgkmcnt(1)
	v_mfma_f32_16x16x4_f32 v[200:203], v184, v64, v[200:203]
	s_waitcnt lgkmcnt(1)
	v_mfma_f32_16x16x4_f32 v[240:243], v185, v65, v[240:243]
	s_waitcnt lgkmcnt(1)
	v_mfma_f32_16x16x4_f32 v[200:203], v186, v66, v[200:203]
	s_waitcnt lgkmcnt(1)
	v_mfma_f32_16x16x4_f32 v[240:243], v187, v67, v[240:243]
	s_waitcnt lgkmcnt(0)
	v_mfma_f32_16x16x4_f32 v[200:203], v188, v68, v[200:203]
	s_waitcnt lgkmcnt(0)
	v_mfma_f32_16x16x4_f32 v[240:243], v189, v69, v[240:243]
	s_waitcnt lgkmcnt(0)
	v_mfma_f32_16x16x4_f32 v[200:203], v190, v70, v[200:203]
	s_waitcnt lgkmcnt(0)
; DI unsigned pk2(float a, float b) { f32x2_t v = {a, b}; return __builtin_bit_cast(unsigned, __builtin_convertvector(v, bf16x2_t)); }
; DI float bf2f(unsigned x) { return __uint_as_float(x << 16); }
; DI float gelu_tanh(float v) { const float z = 0.7978845608028654f * (v + 0.044715f * v * v * v); const float th = 1.0f - 2.0f * __builtin_amdgcn_rcpf(__builtin_amdgcn_exp2f(2.8853900817779268f * z) + 1.0f); return 0.5f * v * (1.0f + th); }
; DI void s5_pass3_item(const Params& P, int bitem, unsigned char* smem) {
;     ...
;     for (int sub = 0; sub < 4; ++sub) {
;         s5_bu16(ubs[sub], af, xs, r, q);
;         float uv[4];
; #pragma unroll
;         for (int j = 0; j < 4; ++j) uv[j] = bf2f(uvs[sub][j]);
;         asm volatile("s_waitcnt lgkmcnt(0)" ::: "memory");
; #pragma unroll
;         for (int tt = 0; tt < 16; ++tt) { const float bur = xs[lane * 17 + tt], bui = xs[(64 + lane) * 17 + tt];
;             const float nxr = ab[0] * xr - ab[1] * xi + bur, nxi = ab[0] * xi + ab[1] * xr + bui; xr = nxr; xi = nxi;
;             xs[lane * 17 + tt] = xr; xs[(64 + lane) * 17 + tt] = xi; }
;         asm volatile("s_waitcnt lgkmcnt(0)" ::: "memory");
;         f32x4 ya[4];
; #pragma unroll
;         for (int j = 0; j < 4; ++j) ya[j] = (f32x4){0.f, 0.f, 0.f, 0.f};
; #pragma unroll
;         for (int i = 0; i < 32; ++i) { const float a = xs[(4 * i + q) * 17 + r]; ya[i & 3] = __builtin_amdgcn_mfma_f32_16x16x4f32(a, cB[i], ya[i & 3], 0, 0, 0); }
;         const f32x4 y = (ya[0] + ya[1]) + (ya[2] + ya[3]);
; #pragma unroll
;         for (int j = 0; j < 4; ++j) { const int tl = sub * 16 + 4 * q + j; const float v = y[j] + dsk * uv[j];
;             HG[(size_t)(b * TT + ch * 64 + tl) * 1024 + grp * 16 + r] = (bf16_t)(pk2(gelu_tanh(v), 0.f) & 0xffffu); }
	v_mfma_f32_16x16x4_f32 v[240:243], v191, v71, v[240:243]
	s_nop 9
	v_add_f32_e32 v1, v200, v240
	v_add_f32_e32 v2, v201, v241
	v_add_f32_e32 v3, v202, v242
	v_add_f32_e32 v4, v203, v243
	v_fmac_f32_e32 v1, v76, v108
	v_fmac_f32_e32 v2, v76, v109
	v_fmac_f32_e32 v3, v76, v110
	v_fmac_f32_e32 v4, v76, v111
	v_mul_f32_e32 v5, 0x3d372713, v1
	v_mul_f32_e32 v6, 0x3d372713, v2
	v_mul_f32_e32 v7, 0x3d372713, v3
	v_mul_f32_e32 v246, 0x3d372713, v4
	v_mul_f32_e32 v5, v1, v5
	v_mul_f32_e32 v6, v2, v6
	v_mul_f32_e32 v7, v3, v7
	v_mul_f32_e32 v246, v4, v246
	v_mul_f32_e32 v194, 0.5, v1
	v_mul_f32_e32 v195, 0.5, v2
	v_mul_f32_e32 v196, 0.5, v3
	v_mul_f32_e32 v197, 0.5, v4
	v_fma_f32 v1, v1, v5, v1
	v_fma_f32 v2, v2, v6, v2
	v_fma_f32 v3, v3, v7, v3
	v_fma_f32 v4, v4, v246, v4
	v_mul_f32_e32 v1, 0x3f4c422a, v1
	v_mul_f32_e32 v2, 0x3f4c422a, v2
	v_mul_f32_e32 v3, 0x3f4c422a, v3
	v_mul_f32_e32 v4, 0x3f4c422a, v4
	v_mul_f32_e32 v1, 0x4038aa3b, v1
	v_mul_f32_e32 v2, 0x4038aa3b, v2
	v_mul_f32_e32 v3, 0x4038aa3b, v3
	v_mul_f32_e32 v4, 0x4038aa3b, v4
	v_exp_f32_e32 v1, v1
	v_exp_f32_e32 v2, v2
	v_exp_f32_e32 v3, v3
	v_exp_f32_e32 v4, v4
	v_add_f32_e32 v1, 1.0, v1
	v_add_f32_e32 v2, 1.0, v2
	v_add_f32_e32 v3, 1.0, v3
	v_add_f32_e32 v4, 1.0, v4
	v_rcp_f32_e32 v1, v1
	v_rcp_f32_e32 v2, v2
	v_rcp_f32_e32 v3, v3
	v_rcp_f32_e32 v4, v4
	v_fma_f32 v1, v1, -2.0, 1.0
	v_fma_f32 v2, v2, -2.0, 1.0
	v_fma_f32 v3, v3, -2.0, 1.0
	v_fma_f32 v4, v4, -2.0, 1.0
	v_add_f32_e32 v1, 1.0, v1
	v_add_f32_e32 v2, 1.0, v2
	v_add_f32_e32 v3, 1.0, v3
	v_add_f32_e32 v4, 1.0, v4
	v_mul_f32_e32 v1, v194, v1
	v_mul_f32_e32 v2, v195, v2
	v_mul_f32_e32 v3, v196, v3
	v_mul_f32_e32 v4, v197, v4
	v_cvt_pk_bf16_f32 v1, v1, v1
	v_cvt_pk_bf16_f32 v2, v2, v2
	v_cvt_pk_bf16_f32 v3, v3, v3
	v_cvt_pk_bf16_f32 v4, v4, v4
	global_store_short v198, v1, s[28:29] offset:-4096
	global_store_short v198, v2, s[28:29] offset:-2048
	global_store_short v198, v3, s[28:29] offset:0
	global_store_short v198, v4, s[28:29] offset:2048
	s_add_u32 s28, s28, 0x8000
	s_addc_u32 s29, s29, 0
	v_mfma_f32_16x16x32_bf16 v[160:163], v[8:11], v[96:99], 0
	v_mfma_f32_16x16x32_bf16 v[164:167], v[12:15], v[96:99], 0
	v_mfma_f32_16x16x32_bf16 v[168:171], v[16:19], v[96:99], 0
	v_mfma_f32_16x16x32_bf16 v[172:175], v[20:23], v[96:99], 0
	v_mfma_f32_16x16x32_bf16 v[176:179], v[24:27], v[96:99], 0
	v_mfma_f32_16x16x32_bf16 v[180:183], v[28:31], v[96:99], 0
	v_mfma_f32_16x16x32_bf16 v[184:187], v[32:35], v[96:99], 0
	v_mfma_f32_16x16x32_bf16 v[188:191], v[36:39], v[96:99], 0
	s_nop 1
	ds_write_b128 v77, v[160:163] offset:0
	ds_write_b128 v77, v[164:167] offset:64
	ds_write_b128 v77, v[168:171] offset:128
	ds_write_b128 v77, v[172:175] offset:192
	ds_write_b128 v77, v[176:179] offset:256
	ds_write_b128 v77, v[180:183] offset:320
	ds_write_b128 v77, v[184:187] offset:384
	ds_write_b128 v77, v[188:191] offset:448
	ds_read_addtid_b32 v208 offset:0
	ds_read_addtid_b32 v224 offset:256
	ds_read_addtid_b32 v209 offset:528
	ds_read_addtid_b32 v225 offset:784
	ds_read_addtid_b32 v210 offset:1056
	ds_read_addtid_b32 v226 offset:1312
	ds_read_addtid_b32 v211 offset:1584
	ds_read_addtid_b32 v227 offset:1840
	ds_read_addtid_b32 v212 offset:2112
	ds_read_addtid_b32 v228 offset:2368
	ds_read_addtid_b32 v213 offset:2640
	ds_read_addtid_b32 v229 offset:2896
	ds_read_addtid_b32 v214 offset:3168
	ds_read_addtid_b32 v230 offset:3424
	ds_read_addtid_b32 v215 offset:3696
	ds_read_addtid_b32 v231 offset:3952
	ds_read_addtid_b32 v216 offset:4224
	ds_read_addtid_b32 v232 offset:4480
	ds_read_addtid_b32 v217 offset:4752
	ds_read_addtid_b32 v233 offset:5008
	ds_read_addtid_b32 v218 offset:5280
	ds_read_addtid_b32 v234 offset:5536
	ds_read_addtid_b32 v219 offset:5808
	ds_read_addtid_b32 v235 offset:6064
	ds_read_addtid_b32 v220 offset:6336
	ds_read_addtid_b32 v236 offset:6592
	ds_read_addtid_b32 v221 offset:6864
	ds_read_addtid_b32 v237 offset:7120
	ds_read_addtid_b32 v222 offset:7392
	ds_read_addtid_b32 v238 offset:7648
	ds_read_addtid_b32 v223 offset:7920
	ds_read_addtid_b32 v239 offset:8176
	s_waitcnt lgkmcnt(15)
	v_mul_f32_e32 v194, v73, v193
	v_mul_f32_e32 v195, v73, v192
	v_fma_f32 v194, v72, v192, -v194
	v_fma_f32 v195, v72, v193, v195
	v_add_f32_e32 v208, v194, v208
	v_add_f32_e32 v224, v195, v224
	ds_write_addtid_b32 v208 offset:0
	ds_write_addtid_b32 v224 offset:256
	s_waitcnt lgkmcnt(15)
	v_mul_f32_e32 v194, v73, v224
	v_mul_f32_e32 v195, v73, v208
	v_fma_f32 v194, v72, v208, -v194
	v_fma_f32 v195, v72, v224, v195
	v_add_f32_e32 v209, v194, v209
	v_add_f32_e32 v225, v195, v225
	ds_write_addtid_b32 v209 offset:528
	ds_write_addtid_b32 v225 offset:784
	s_waitcnt lgkmcnt(15)
	v_mul_f32_e32 v194, v73, v225
	v_mul_f32_e32 v195, v73, v209
	v_fma_f32 v194, v72, v209, -v194
	v_fma_f32 v195, v72, v225, v195
	v_add_f32_e32 v210, v194, v210
	v_add_f32_e32 v226, v195, v226
	ds_write_addtid_b32 v210 offset:1056
	ds_write_addtid_b32 v226 offset:1312
	s_waitcnt lgkmcnt(15)
	v_mul_f32_e32 v194, v73, v226
	v_mul_f32_e32 v195, v73, v210
	v_fma_f32 v194, v72, v210, -v194
	v_fma_f32 v195, v72, v226, v195
	v_add_f32_e32 v211, v194, v211
	v_add_f32_e32 v227, v195, v227
	ds_write_addtid_b32 v211 offset:1584
	ds_write_addtid_b32 v227 offset:1840
	s_waitcnt lgkmcnt(15)
	v_mul_f32_e32 v194, v73, v227
	v_mul_f32_e32 v195, v73, v211
	v_fma_f32 v194, v72, v211, -v194
	v_fma_f32 v195, v72, v227, v195
	v_add_f32_e32 v212, v194, v212
	v_add_f32_e32 v228, v195, v228
	ds_write_addtid_b32 v212 offset:2112
	ds_write_addtid_b32 v228 offset:2368
	s_waitcnt lgkmcnt(15)
; DI void s5_pass3_item(const Params& P, int bitem, unsigned char* smem) {
;     ...
; #pragma unroll
;         for (int tt = 0; tt < 16; ++tt) { const float bur = xs[lane * 17 + tt], bui = xs[(64 + lane) * 17 + tt];
;             const float nxr = ab[0] * xr - ab[1] * xi + bur, nxi = ab[0] * xi + ab[1] * xr + bui; xr = nxr; xi = nxi;
;             xs[lane * 17 + tt] = xr; xs[(64 + lane) * 17 + tt] = xi; }
;         asm volatile("s_waitcnt lgkmcnt(0)" ::: "memory");
;         f32x4 ya[4];
; #pragma unroll
;         for (int j = 0; j < 4; ++j) ya[j] = (f32x4){0.f, 0.f, 0.f, 0.f};
; #pragma unroll
;         for (int i = 0; i < 32; ++i) { const float a = xs[(4 * i + q) * 17 + r]; ya[i & 3] = __builtin_amdgcn_mfma_f32_16x16x4f32(a, cB[i], ya[i & 3], 0, 0, 0); }
;         const f32x4 y = (ya[0] + ya[1]) + (ya[2] + ya[3]);
	v_mul_f32_e32 v194, v73, v228
	v_mul_f32_e32 v195, v73, v212
	v_fma_f32 v194, v72, v212, -v194
	v_fma_f32 v195, v72, v228, v195
	v_add_f32_e32 v213, v194, v213
	v_add_f32_e32 v229, v195, v229
	ds_write_addtid_b32 v213 offset:2640
	ds_write_addtid_b32 v229 offset:2896
	s_waitcnt lgkmcnt(15)
	v_mul_f32_e32 v194, v73, v229
	v_mul_f32_e32 v195, v73, v213
	v_fma_f32 v194, v72, v213, -v194
	v_fma_f32 v195, v72, v229, v195
	v_add_f32_e32 v214, v194, v214
	v_add_f32_e32 v230, v195, v230
	ds_write_addtid_b32 v214 offset:3168
	ds_write_addtid_b32 v230 offset:3424
	s_waitcnt lgkmcnt(15)
	v_mul_f32_e32 v194, v73, v230
	v_mul_f32_e32 v195, v73, v214
	v_fma_f32 v194, v72, v214, -v194
	v_fma_f32 v195, v72, v230, v195
	v_add_f32_e32 v215, v194, v215
	v_add_f32_e32 v231, v195, v231
	ds_write_addtid_b32 v215 offset:3696
	ds_write_addtid_b32 v231 offset:3952
	s_waitcnt lgkmcnt(15)
	v_mul_f32_e32 v194, v73, v231
	v_mul_f32_e32 v195, v73, v215
	v_fma_f32 v194, v72, v215, -v194
	v_fma_f32 v195, v72, v231, v195
	v_add_f32_e32 v216, v194, v216
	v_add_f32_e32 v232, v195, v232
	ds_write_addtid_b32 v216 offset:4224
	ds_write_addtid_b32 v232 offset:4480
	s_waitcnt lgkmcnt(15)
	v_mul_f32_e32 v194, v73, v232
	v_mul_f32_e32 v195, v73, v216
	v_fma_f32 v194, v72, v216, -v194
	v_fma_f32 v195, v72, v232, v195
	v_add_f32_e32 v217, v194, v217
	v_add_f32_e32 v233, v195, v233
	ds_write_addtid_b32 v217 offset:4752
	ds_write_addtid_b32 v233 offset:5008
	s_waitcnt lgkmcnt(15)
	v_mul_f32_e32 v194, v73, v233
	v_mul_f32_e32 v195, v73, v217
	v_fma_f32 v194, v72, v217, -v194
	v_fma_f32 v195, v72, v233, v195
	v_add_f32_e32 v218, v194, v218
	v_add_f32_e32 v234, v195, v234
	ds_write_addtid_b32 v218 offset:5280
	ds_write_addtid_b32 v234 offset:5536
	s_waitcnt lgkmcnt(15)
	v_mul_f32_e32 v194, v73, v234
	v_mul_f32_e32 v195, v73, v218
	v_fma_f32 v194, v72, v218, -v194
	v_fma_f32 v195, v72, v234, v195
	v_add_f32_e32 v219, v194, v219
	v_add_f32_e32 v235, v195, v235
	ds_write_addtid_b32 v219 offset:5808
	ds_write_addtid_b32 v235 offset:6064
	s_waitcnt lgkmcnt(15)
	v_mul_f32_e32 v194, v73, v235
	v_mul_f32_e32 v195, v73, v219
	v_fma_f32 v194, v72, v219, -v194
	v_fma_f32 v195, v72, v235, v195
	v_add_f32_e32 v220, v194, v220
	v_add_f32_e32 v236, v195, v236
	ds_write_addtid_b32 v220 offset:6336
	ds_write_addtid_b32 v236 offset:6592
	s_waitcnt lgkmcnt(15)
	v_mul_f32_e32 v194, v73, v236
	v_mul_f32_e32 v195, v73, v220
	v_fma_f32 v194, v72, v220, -v194
	v_fma_f32 v195, v72, v236, v195
	v_add_f32_e32 v221, v194, v221
	v_add_f32_e32 v237, v195, v237
	ds_write_addtid_b32 v221 offset:6864
	ds_write_addtid_b32 v237 offset:7120
	s_waitcnt lgkmcnt(15)
	v_mul_f32_e32 v194, v73, v237
	v_mul_f32_e32 v195, v73, v221
	v_fma_f32 v194, v72, v221, -v194
	v_fma_f32 v195, v72, v237, v195
	v_add_f32_e32 v222, v194, v222
	v_add_f32_e32 v238, v195, v238
	ds_write_addtid_b32 v222 offset:7392
	ds_write_addtid_b32 v238 offset:7648
	s_waitcnt lgkmcnt(15)
	v_mul_f32_e32 v194, v73, v238
	v_mul_f32_e32 v195, v73, v222
	v_fma_f32 v194, v72, v222, -v194
	v_fma_f32 v195, v72, v238, v195
	v_add_f32_e32 v223, v194, v223
	v_add_f32_e32 v239, v195, v239
	ds_write_addtid_b32 v223 offset:7920
	ds_write_addtid_b32 v239 offset:8176
	v_mov_b32_e32 v192, v223
	v_mov_b32_e32 v193, v239
	ds_read_b128 v[160:163], v77 offset:0
	ds_read_b128 v[164:167], v77 offset:64
	ds_read_b128 v[168:171], v77 offset:128
	ds_read_b128 v[172:175], v77 offset:192
	ds_read_b128 v[176:179], v77 offset:256
	ds_read_b128 v[180:183], v77 offset:320
	ds_read_b128 v[184:187], v77 offset:384
	ds_read_b128 v[188:191], v77 offset:448
	s_waitcnt lgkmcnt(7)
	v_mfma_f32_16x16x4_f32 v[200:203], v160, v40, 0
	s_waitcnt lgkmcnt(7)
	v_mfma_f32_16x16x4_f32 v[240:243], v161, v41, 0
	s_waitcnt lgkmcnt(7)
	v_mfma_f32_16x16x4_f32 v[200:203], v162, v42, v[200:203]
	s_waitcnt lgkmcnt(7)
	v_mfma_f32_16x16x4_f32 v[240:243], v163, v43, v[240:243]
	s_waitcnt lgkmcnt(6)
	v_mfma_f32_16x16x4_f32 v[200:203], v164, v44, v[200:203]
	s_waitcnt lgkmcnt(6)
	v_mfma_f32_16x16x4_f32 v[240:243], v165, v45, v[240:243]
	s_waitcnt lgkmcnt(6)
	v_mfma_f32_16x16x4_f32 v[200:203], v166, v46, v[200:203]
	s_waitcnt lgkmcnt(6)
	v_mfma_f32_16x16x4_f32 v[240:243], v167, v47, v[240:243]
	s_waitcnt lgkmcnt(5)
	v_mfma_f32_16x16x4_f32 v[200:203], v168, v48, v[200:203]
	s_waitcnt lgkmcnt(5)
	v_mfma_f32_16x16x4_f32 v[240:243], v169, v49, v[240:243]
	s_waitcnt lgkmcnt(5)
	v_mfma_f32_16x16x4_f32 v[200:203], v170, v50, v[200:203]
	s_waitcnt lgkmcnt(5)
	v_mfma_f32_16x16x4_f32 v[240:243], v171, v51, v[240:243]
	s_waitcnt lgkmcnt(4)
	v_mfma_f32_16x16x4_f32 v[200:203], v172, v52, v[200:203]
	s_waitcnt lgkmcnt(4)
	v_mfma_f32_16x16x4_f32 v[240:243], v173, v53, v[240:243]
	s_waitcnt lgkmcnt(4)
	v_mfma_f32_16x16x4_f32 v[200:203], v174, v54, v[200:203]
	s_waitcnt lgkmcnt(4)
	v_mfma_f32_16x16x4_f32 v[240:243], v175, v55, v[240:243]
	s_waitcnt lgkmcnt(3)
	v_mfma_f32_16x16x4_f32 v[200:203], v176, v56, v[200:203]
	s_waitcnt lgkmcnt(3)
	v_mfma_f32_16x16x4_f32 v[240:243], v177, v57, v[240:243]
	s_waitcnt lgkmcnt(3)
	v_mfma_f32_16x16x4_f32 v[200:203], v178, v58, v[200:203]
	s_waitcnt lgkmcnt(3)
	v_mfma_f32_16x16x4_f32 v[240:243], v179, v59, v[240:243]
	s_waitcnt lgkmcnt(2)
	v_mfma_f32_16x16x4_f32 v[200:203], v180, v60, v[200:203]
	s_waitcnt lgkmcnt(2)
	v_mfma_f32_16x16x4_f32 v[240:243], v181, v61, v[240:243]
	s_waitcnt lgkmcnt(2)
	v_mfma_f32_16x16x4_f32 v[200:203], v182, v62, v[200:203]
	s_waitcnt lgkmcnt(2)
	v_mfma_f32_16x16x4_f32 v[240:243], v183, v63, v[240:243]
	s_waitcnt lgkmcnt(1)
	v_mfma_f32_16x16x4_f32 v[200:203], v184, v64, v[200:203]
	s_waitcnt lgkmcnt(1)
	v_mfma_f32_16x16x4_f32 v[240:243], v185, v65, v[240:243]
	s_waitcnt lgkmcnt(1)
; DI unsigned pk2(float a, float b) { f32x2_t v = {a, b}; return __builtin_bit_cast(unsigned, __builtin_convertvector(v, bf16x2_t)); }
; DI float bf2f(unsigned x) { return __uint_as_float(x << 16); }
; DI float gelu_tanh(float v) { const float z = 0.7978845608028654f * (v + 0.044715f * v * v * v); const float th = 1.0f - 2.0f * __builtin_amdgcn_rcpf(__builtin_amdgcn_exp2f(2.8853900817779268f * z) + 1.0f); return 0.5f * v * (1.0f + th); }
; DI void s5_pass3_item(const Params& P, int bitem, unsigned char* smem) {
;     ...
;     for (int sub = 0; sub < 4; ++sub) {
;         s5_bu16(ubs[sub], af, xs, r, q);
;         float uv[4];
; #pragma unroll
;         for (int j = 0; j < 4; ++j) uv[j] = bf2f(uvs[sub][j]);
;         asm volatile("s_waitcnt lgkmcnt(0)" ::: "memory");
; #pragma unroll
;         for (int tt = 0; tt < 16; ++tt) { const float bur = xs[lane * 17 + tt], bui = xs[(64 + lane) * 17 + tt];
;             const float nxr = ab[0] * xr - ab[1] * xi + bur, nxi = ab[0] * xi + ab[1] * xr + bui; xr = nxr; xi = nxi;
;             xs[lane * 17 + tt] = xr; xs[(64 + lane) * 17 + tt] = xi; }
;         asm volatile("s_waitcnt lgkmcnt(0)" ::: "memory");
;         f32x4 ya[4];
; #pragma unroll
;         for (int j = 0; j < 4; ++j) ya[j] = (f32x4){0.f, 0.f, 0.f, 0.f};
; #pragma unroll
;         for (int i = 0; i < 32; ++i) { const float a = xs[(4 * i + q) * 17 + r]; ya[i & 3] = __builtin_amdgcn_mfma_f32_16x16x4f32(a, cB[i], ya[i & 3], 0, 0, 0); }
;         const f32x4 y = (ya[0] + ya[1]) + (ya[2] + ya[3]);
; #pragma unroll
;         for (int j = 0; j < 4; ++j) { const int tl = sub * 16 + 4 * q + j; const float v = y[j] + dsk * uv[j];
;             HG[(size_t)(b * TT + ch * 64 + tl) * 1024 + grp * 16 + r] = (bf16_t)(pk2(gelu_tanh(v), 0.f) & 0xffffu); }
	v_mfma_f32_16x16x4_f32 v[200:203], v186, v66, v[200:203]
	s_waitcnt lgkmcnt(1)
	v_mfma_f32_16x16x4_f32 v[240:243], v187, v67, v[240:243]
	s_waitcnt lgkmcnt(0)
	v_mfma_f32_16x16x4_f32 v[200:203], v188, v68, v[200:203]
	s_waitcnt lgkmcnt(0)
	v_mfma_f32_16x16x4_f32 v[240:243], v189, v69, v[240:243]
	s_waitcnt lgkmcnt(0)
	v_mfma_f32_16x16x4_f32 v[200:203], v190, v70, v[200:203]
	s_waitcnt lgkmcnt(0)
	v_mfma_f32_16x16x4_f32 v[240:243], v191, v71, v[240:243]
	s_nop 9
	v_add_f32_e32 v1, v200, v240
	v_add_f32_e32 v2, v201, v241
	v_add_f32_e32 v3, v202, v242
	v_add_f32_e32 v4, v203, v243
	v_fmac_f32_e32 v1, v76, v112
	v_fmac_f32_e32 v2, v76, v113
	v_fmac_f32_e32 v3, v76, v114
	v_fmac_f32_e32 v4, v76, v115
	v_mul_f32_e32 v5, 0x3d372713, v1
	v_mul_f32_e32 v6, 0x3d372713, v2
	v_mul_f32_e32 v7, 0x3d372713, v3
	v_mul_f32_e32 v246, 0x3d372713, v4
	v_mul_f32_e32 v5, v1, v5
	v_mul_f32_e32 v6, v2, v6
	v_mul_f32_e32 v7, v3, v7
	v_mul_f32_e32 v246, v4, v246
	v_mul_f32_e32 v194, 0.5, v1
	v_mul_f32_e32 v195, 0.5, v2
	v_mul_f32_e32 v196, 0.5, v3
	v_mul_f32_e32 v197, 0.5, v4
	v_fma_f32 v1, v1, v5, v1
	v_fma_f32 v2, v2, v6, v2
	v_fma_f32 v3, v3, v7, v3
	v_fma_f32 v4, v4, v246, v4
	v_mul_f32_e32 v1, 0x3f4c422a, v1
	v_mul_f32_e32 v2, 0x3f4c422a, v2
	v_mul_f32_e32 v3, 0x3f4c422a, v3
	v_mul_f32_e32 v4, 0x3f4c422a, v4
	v_mul_f32_e32 v1, 0x4038aa3b, v1
	v_mul_f32_e32 v2, 0x4038aa3b, v2
	v_mul_f32_e32 v3, 0x4038aa3b, v3
	v_mul_f32_e32 v4, 0x4038aa3b, v4
	v_exp_f32_e32 v1, v1
	v_exp_f32_e32 v2, v2
	v_exp_f32_e32 v3, v3
	v_exp_f32_e32 v4, v4
	v_add_f32_e32 v1, 1.0, v1
	v_add_f32_e32 v2, 1.0, v2
	v_add_f32_e32 v3, 1.0, v3
	v_add_f32_e32 v4, 1.0, v4
	v_rcp_f32_e32 v1, v1
	v_rcp_f32_e32 v2, v2
	v_rcp_f32_e32 v3, v3
	v_rcp_f32_e32 v4, v4
	v_fma_f32 v1, v1, -2.0, 1.0
	v_fma_f32 v2, v2, -2.0, 1.0
	v_fma_f32 v3, v3, -2.0, 1.0
	v_fma_f32 v4, v4, -2.0, 1.0
	v_add_f32_e32 v1, 1.0, v1
	v_add_f32_e32 v2, 1.0, v2
	v_add_f32_e32 v3, 1.0, v3
	v_add_f32_e32 v4, 1.0, v4
	v_mul_f32_e32 v1, v194, v1
	v_mul_f32_e32 v2, v195, v2
	v_mul_f32_e32 v3, v196, v3
	v_mul_f32_e32 v4, v197, v4
	v_cvt_pk_bf16_f32 v1, v1, v1
	v_cvt_pk_bf16_f32 v2, v2, v2
	v_cvt_pk_bf16_f32 v3, v3, v3
	v_cvt_pk_bf16_f32 v4, v4, v4
	global_store_short v198, v1, s[28:29] offset:-4096
	global_store_short v198, v2, s[28:29] offset:-2048
	global_store_short v198, v3, s[28:29] offset:0
	global_store_short v198, v4, s[28:29] offset:2048
	s_add_u32 s28, s28, 0x8000
	s_addc_u32 s29, s29, 0
	v_mfma_f32_16x16x32_bf16 v[160:163], v[8:11], v[100:103], 0
	v_mfma_f32_16x16x32_bf16 v[164:167], v[12:15], v[100:103], 0
	v_mfma_f32_16x16x32_bf16 v[168:171], v[16:19], v[100:103], 0
	v_mfma_f32_16x16x32_bf16 v[172:175], v[20:23], v[100:103], 0
	v_mfma_f32_16x16x32_bf16 v[176:179], v[24:27], v[100:103], 0
	v_mfma_f32_16x16x32_bf16 v[180:183], v[28:31], v[100:103], 0
	v_mfma_f32_16x16x32_bf16 v[184:187], v[32:35], v[100:103], 0
	v_mfma_f32_16x16x32_bf16 v[188:191], v[36:39], v[100:103], 0
	s_nop 1
	ds_write_b128 v77, v[160:163] offset:0
	ds_write_b128 v77, v[164:167] offset:64
	ds_write_b128 v77, v[168:171] offset:128
	ds_write_b128 v77, v[172:175] offset:192
	ds_write_b128 v77, v[176:179] offset:256
	ds_write_b128 v77, v[180:183] offset:320
	ds_write_b128 v77, v[184:187] offset:384
	ds_write_b128 v77, v[188:191] offset:448
	ds_read_addtid_b32 v208 offset:0
	ds_read_addtid_b32 v224 offset:256
	ds_read_addtid_b32 v209 offset:528
	ds_read_addtid_b32 v225 offset:784
	ds_read_addtid_b32 v210 offset:1056
	ds_read_addtid_b32 v226 offset:1312
	ds_read_addtid_b32 v211 offset:1584
	ds_read_addtid_b32 v227 offset:1840
	ds_read_addtid_b32 v212 offset:2112
	ds_read_addtid_b32 v228 offset:2368
	ds_read_addtid_b32 v213 offset:2640
	ds_read_addtid_b32 v229 offset:2896
	ds_read_addtid_b32 v214 offset:3168
	ds_read_addtid_b32 v230 offset:3424
	ds_read_addtid_b32 v215 offset:3696
	ds_read_addtid_b32 v231 offset:3952
	ds_read_addtid_b32 v216 offset:4224
	ds_read_addtid_b32 v232 offset:4480
	ds_read_addtid_b32 v217 offset:4752
	ds_read_addtid_b32 v233 offset:5008
	ds_read_addtid_b32 v218 offset:5280
	ds_read_addtid_b32 v234 offset:5536
	ds_read_addtid_b32 v219 offset:5808
	ds_read_addtid_b32 v235 offset:6064
	ds_read_addtid_b32 v220 offset:6336
	ds_read_addtid_b32 v236 offset:6592
	ds_read_addtid_b32 v221 offset:6864
	ds_read_addtid_b32 v237 offset:7120
	ds_read_addtid_b32 v222 offset:7392
	ds_read_addtid_b32 v238 offset:7648
	ds_read_addtid_b32 v223 offset:7920
	ds_read_addtid_b32 v239 offset:8176
	s_waitcnt lgkmcnt(15)
	v_mul_f32_e32 v194, v73, v193
	v_mul_f32_e32 v195, v73, v192
	v_fma_f32 v194, v72, v192, -v194
	v_fma_f32 v195, v72, v193, v195
	v_add_f32_e32 v208, v194, v208
	v_add_f32_e32 v224, v195, v224
	ds_write_addtid_b32 v208 offset:0
	ds_write_addtid_b32 v224 offset:256
	s_waitcnt lgkmcnt(15)
	v_mul_f32_e32 v194, v73, v224
	v_mul_f32_e32 v195, v73, v208
	v_fma_f32 v194, v72, v208, -v194
	v_fma_f32 v195, v72, v224, v195
	v_add_f32_e32 v209, v194, v209
	v_add_f32_e32 v225, v195, v225
	ds_write_addtid_b32 v209 offset:528
	ds_write_addtid_b32 v225 offset:784
	s_waitcnt lgkmcnt(15)
	v_mul_f32_e32 v194, v73, v225
	v_mul_f32_e32 v195, v73, v209
	v_fma_f32 v194, v72, v209, -v194
	v_fma_f32 v195, v72, v225, v195
	v_add_f32_e32 v210, v194, v210
	v_add_f32_e32 v226, v195, v226
	ds_write_addtid_b32 v210 offset:1056
	ds_write_addtid_b32 v226 offset:1312
	s_waitcnt lgkmcnt(15)
	v_mul_f32_e32 v194, v73, v226
	v_mul_f32_e32 v195, v73, v210
	v_fma_f32 v194, v72, v210, -v194
	v_fma_f32 v195, v72, v226, v195
	v_add_f32_e32 v211, v194, v211
	v_add_f32_e32 v227, v195, v227
	ds_write_addtid_b32 v211 offset:1584
	ds_write_addtid_b32 v227 offset:1840
	s_waitcnt lgkmcnt(15)
; DI void s5_pass3_item(const Params& P, int bitem, unsigned char* smem) {
;     ...
; #pragma unroll
;         for (int tt = 0; tt < 16; ++tt) { const float bur = xs[lane * 17 + tt], bui = xs[(64 + lane) * 17 + tt];
;             const float nxr = ab[0] * xr - ab[1] * xi + bur, nxi = ab[0] * xi + ab[1] * xr + bui; xr = nxr; xi = nxi;
;             xs[lane * 17 + tt] = xr; xs[(64 + lane) * 17 + tt] = xi; }
;         asm volatile("s_waitcnt lgkmcnt(0)" ::: "memory");
;         f32x4 ya[4];
; #pragma unroll
;         for (int j = 0; j < 4; ++j) ya[j] = (f32x4){0.f, 0.f, 0.f, 0.f};
; #pragma unroll
;         for (int i = 0; i < 32; ++i) { const float a = xs[(4 * i + q) * 17 + r]; ya[i & 3] = __builtin_amdgcn_mfma_f32_16x16x4f32(a, cB[i], ya[i & 3], 0, 0, 0); }
;         const f32x4 y = (ya[0] + ya[1]) + (ya[2] + ya[3]);
	v_mul_f32_e32 v194, v73, v227
	v_mul_f32_e32 v195, v73, v211
	v_fma_f32 v194, v72, v211, -v194
	v_fma_f32 v195, v72, v227, v195
	v_add_f32_e32 v212, v194, v212
	v_add_f32_e32 v228, v195, v228
	ds_write_addtid_b32 v212 offset:2112
	ds_write_addtid_b32 v228 offset:2368
	s_waitcnt lgkmcnt(15)
	v_mul_f32_e32 v194, v73, v228
	v_mul_f32_e32 v195, v73, v212
	v_fma_f32 v194, v72, v212, -v194
	v_fma_f32 v195, v72, v228, v195
	v_add_f32_e32 v213, v194, v213
	v_add_f32_e32 v229, v195, v229
	ds_write_addtid_b32 v213 offset:2640
	ds_write_addtid_b32 v229 offset:2896
	s_waitcnt lgkmcnt(15)
	v_mul_f32_e32 v194, v73, v229
	v_mul_f32_e32 v195, v73, v213
	v_fma_f32 v194, v72, v213, -v194
	v_fma_f32 v195, v72, v229, v195
	v_add_f32_e32 v214, v194, v214
	v_add_f32_e32 v230, v195, v230
	ds_write_addtid_b32 v214 offset:3168
	ds_write_addtid_b32 v230 offset:3424
	s_waitcnt lgkmcnt(15)
	v_mul_f32_e32 v194, v73, v230
	v_mul_f32_e32 v195, v73, v214
	v_fma_f32 v194, v72, v214, -v194
	v_fma_f32 v195, v72, v230, v195
	v_add_f32_e32 v215, v194, v215
	v_add_f32_e32 v231, v195, v231
	ds_write_addtid_b32 v215 offset:3696
	ds_write_addtid_b32 v231 offset:3952
	s_waitcnt lgkmcnt(15)
	v_mul_f32_e32 v194, v73, v231
	v_mul_f32_e32 v195, v73, v215
	v_fma_f32 v194, v72, v215, -v194
	v_fma_f32 v195, v72, v231, v195
	v_add_f32_e32 v216, v194, v216
	v_add_f32_e32 v232, v195, v232
	ds_write_addtid_b32 v216 offset:4224
	ds_write_addtid_b32 v232 offset:4480
	s_waitcnt lgkmcnt(15)
	v_mul_f32_e32 v194, v73, v232
	v_mul_f32_e32 v195, v73, v216
	v_fma_f32 v194, v72, v216, -v194
	v_fma_f32 v195, v72, v232, v195
	v_add_f32_e32 v217, v194, v217
	v_add_f32_e32 v233, v195, v233
	ds_write_addtid_b32 v217 offset:4752
	ds_write_addtid_b32 v233 offset:5008
	s_waitcnt lgkmcnt(15)
	v_mul_f32_e32 v194, v73, v233
	v_mul_f32_e32 v195, v73, v217
	v_fma_f32 v194, v72, v217, -v194
	v_fma_f32 v195, v72, v233, v195
	v_add_f32_e32 v218, v194, v218
	v_add_f32_e32 v234, v195, v234
	ds_write_addtid_b32 v218 offset:5280
	ds_write_addtid_b32 v234 offset:5536
	s_waitcnt lgkmcnt(15)
	v_mul_f32_e32 v194, v73, v234
	v_mul_f32_e32 v195, v73, v218
	v_fma_f32 v194, v72, v218, -v194
	v_fma_f32 v195, v72, v234, v195
	v_add_f32_e32 v219, v194, v219
	v_add_f32_e32 v235, v195, v235
	ds_write_addtid_b32 v219 offset:5808
	ds_write_addtid_b32 v235 offset:6064
	s_waitcnt lgkmcnt(15)
	v_mul_f32_e32 v194, v73, v235
	v_mul_f32_e32 v195, v73, v219
	v_fma_f32 v194, v72, v219, -v194
	v_fma_f32 v195, v72, v235, v195
	v_add_f32_e32 v220, v194, v220
	v_add_f32_e32 v236, v195, v236
	ds_write_addtid_b32 v220 offset:6336
	ds_write_addtid_b32 v236 offset:6592
	s_waitcnt lgkmcnt(15)
	v_mul_f32_e32 v194, v73, v236
	v_mul_f32_e32 v195, v73, v220
	v_fma_f32 v194, v72, v220, -v194
	v_fma_f32 v195, v72, v236, v195
	v_add_f32_e32 v221, v194, v221
	v_add_f32_e32 v237, v195, v237
	ds_write_addtid_b32 v221 offset:6864
	ds_write_addtid_b32 v237 offset:7120
	s_waitcnt lgkmcnt(15)
	v_mul_f32_e32 v194, v73, v237
	v_mul_f32_e32 v195, v73, v221
	v_fma_f32 v194, v72, v221, -v194
	v_fma_f32 v195, v72, v237, v195
	v_add_f32_e32 v222, v194, v222
	v_add_f32_e32 v238, v195, v238
	ds_write_addtid_b32 v222 offset:7392
	ds_write_addtid_b32 v238 offset:7648
	s_waitcnt lgkmcnt(15)
	v_mul_f32_e32 v194, v73, v238
	v_mul_f32_e32 v195, v73, v222
	v_fma_f32 v194, v72, v222, -v194
	v_fma_f32 v195, v72, v238, v195
	v_add_f32_e32 v223, v194, v223
	v_add_f32_e32 v239, v195, v239
	ds_write_addtid_b32 v223 offset:7920
	ds_write_addtid_b32 v239 offset:8176
	v_mov_b32_e32 v192, v223
	v_mov_b32_e32 v193, v239
	ds_read_b128 v[160:163], v77 offset:0
	ds_read_b128 v[164:167], v77 offset:64
	ds_read_b128 v[168:171], v77 offset:128
	ds_read_b128 v[172:175], v77 offset:192
	ds_read_b128 v[176:179], v77 offset:256
	ds_read_b128 v[180:183], v77 offset:320
	ds_read_b128 v[184:187], v77 offset:384
	ds_read_b128 v[188:191], v77 offset:448
	s_waitcnt lgkmcnt(7)
	v_mfma_f32_16x16x4_f32 v[200:203], v160, v40, 0
	s_waitcnt lgkmcnt(7)
	v_mfma_f32_16x16x4_f32 v[240:243], v161, v41, 0
	s_waitcnt lgkmcnt(7)
	v_mfma_f32_16x16x4_f32 v[200:203], v162, v42, v[200:203]
	s_waitcnt lgkmcnt(7)
	v_mfma_f32_16x16x4_f32 v[240:243], v163, v43, v[240:243]
	s_waitcnt lgkmcnt(6)
	v_mfma_f32_16x16x4_f32 v[200:203], v164, v44, v[200:203]
	s_waitcnt lgkmcnt(6)
; DI unsigned pk2(float a, float b) { f32x2_t v = {a, b}; return __builtin_bit_cast(unsigned, __builtin_convertvector(v, bf16x2_t)); }
; DI float gelu_tanh(float v) { const float z = 0.7978845608028654f * (v + 0.044715f * v * v * v); const float th = 1.0f - 2.0f * __builtin_amdgcn_rcpf(__builtin_amdgcn_exp2f(2.8853900817779268f * z) + 1.0f); return 0.5f * v * (1.0f + th); }
; DI void s5_pass3_item(const Params& P, int bitem, unsigned char* smem) {
;     ...
;         f32x4 ya[4];
; #pragma unroll
;         for (int j = 0; j < 4; ++j) ya[j] = (f32x4){0.f, 0.f, 0.f, 0.f};
; #pragma unroll
;         for (int i = 0; i < 32; ++i) { const float a = xs[(4 * i + q) * 17 + r]; ya[i & 3] = __builtin_amdgcn_mfma_f32_16x16x4f32(a, cB[i], ya[i & 3], 0, 0, 0); }
;         const f32x4 y = (ya[0] + ya[1]) + (ya[2] + ya[3]);
; #pragma unroll
;         for (int j = 0; j < 4; ++j) { const int tl = sub * 16 + 4 * q + j; const float v = y[j] + dsk * uv[j];
;             HG[(size_t)(b * TT + ch * 64 + tl) * 1024 + grp * 16 + r] = (bf16_t)(pk2(gelu_tanh(v), 0.f) & 0xffffu); }
;         asm volatile("s_waitcnt lgkmcnt(0)" ::: "memory");
;     }
	v_mfma_f32_16x16x4_f32 v[240:243], v165, v45, v[240:243]
	s_waitcnt lgkmcnt(6)
	v_mfma_f32_16x16x4_f32 v[200:203], v166, v46, v[200:203]
	s_waitcnt lgkmcnt(6)
	v_mfma_f32_16x16x4_f32 v[240:243], v167, v47, v[240:243]
	s_waitcnt lgkmcnt(5)
	v_mfma_f32_16x16x4_f32 v[200:203], v168, v48, v[200:203]
	s_waitcnt lgkmcnt(5)
	v_mfma_f32_16x16x4_f32 v[240:243], v169, v49, v[240:243]
	s_waitcnt lgkmcnt(5)
	v_mfma_f32_16x16x4_f32 v[200:203], v170, v50, v[200:203]
	s_waitcnt lgkmcnt(5)
	v_mfma_f32_16x16x4_f32 v[240:243], v171, v51, v[240:243]
	s_waitcnt lgkmcnt(4)
	v_mfma_f32_16x16x4_f32 v[200:203], v172, v52, v[200:203]
	s_waitcnt lgkmcnt(4)
	v_mfma_f32_16x16x4_f32 v[240:243], v173, v53, v[240:243]
	s_waitcnt lgkmcnt(4)
	v_mfma_f32_16x16x4_f32 v[200:203], v174, v54, v[200:203]
	s_waitcnt lgkmcnt(4)
	v_mfma_f32_16x16x4_f32 v[240:243], v175, v55, v[240:243]
	s_waitcnt lgkmcnt(3)
	v_mfma_f32_16x16x4_f32 v[200:203], v176, v56, v[200:203]
	s_waitcnt lgkmcnt(3)
	v_mfma_f32_16x16x4_f32 v[240:243], v177, v57, v[240:243]
	s_waitcnt lgkmcnt(3)
	v_mfma_f32_16x16x4_f32 v[200:203], v178, v58, v[200:203]
	s_waitcnt lgkmcnt(3)
	v_mfma_f32_16x16x4_f32 v[240:243], v179, v59, v[240:243]
	s_waitcnt lgkmcnt(2)
	v_mfma_f32_16x16x4_f32 v[200:203], v180, v60, v[200:203]
	s_waitcnt lgkmcnt(2)
	v_mfma_f32_16x16x4_f32 v[240:243], v181, v61, v[240:243]
	s_waitcnt lgkmcnt(2)
	v_mfma_f32_16x16x4_f32 v[200:203], v182, v62, v[200:203]
	s_waitcnt lgkmcnt(2)
	v_mfma_f32_16x16x4_f32 v[240:243], v183, v63, v[240:243]
	s_waitcnt lgkmcnt(1)
	v_mfma_f32_16x16x4_f32 v[200:203], v184, v64, v[200:203]
	s_waitcnt lgkmcnt(1)
	v_mfma_f32_16x16x4_f32 v[240:243], v185, v65, v[240:243]
	s_waitcnt lgkmcnt(1)
	v_mfma_f32_16x16x4_f32 v[200:203], v186, v66, v[200:203]
	s_waitcnt lgkmcnt(1)
	v_mfma_f32_16x16x4_f32 v[240:243], v187, v67, v[240:243]
	s_waitcnt lgkmcnt(0)
	v_mfma_f32_16x16x4_f32 v[200:203], v188, v68, v[200:203]
	s_waitcnt lgkmcnt(0)
	v_mfma_f32_16x16x4_f32 v[240:243], v189, v69, v[240:243]
	s_waitcnt lgkmcnt(0)
	v_mfma_f32_16x16x4_f32 v[200:203], v190, v70, v[200:203]
	s_waitcnt lgkmcnt(0)
	v_mfma_f32_16x16x4_f32 v[240:243], v191, v71, v[240:243]
	s_nop 9
	v_add_f32_e32 v1, v200, v240
	v_add_f32_e32 v2, v201, v241
	v_add_f32_e32 v3, v202, v242
	v_add_f32_e32 v4, v203, v243
	v_fmac_f32_e32 v1, v76, v116
	v_fmac_f32_e32 v2, v76, v117
	v_fmac_f32_e32 v3, v76, v118
	v_fmac_f32_e32 v4, v76, v119
	v_mul_f32_e32 v5, 0x3d372713, v1
	v_mul_f32_e32 v6, 0x3d372713, v2
	v_mul_f32_e32 v7, 0x3d372713, v3
	v_mul_f32_e32 v246, 0x3d372713, v4
	v_mul_f32_e32 v5, v1, v5
	v_mul_f32_e32 v6, v2, v6
	v_mul_f32_e32 v7, v3, v7
	v_mul_f32_e32 v246, v4, v246
	v_mul_f32_e32 v194, 0.5, v1
	v_mul_f32_e32 v195, 0.5, v2
	v_mul_f32_e32 v196, 0.5, v3
	v_mul_f32_e32 v197, 0.5, v4
	v_fma_f32 v1, v1, v5, v1
	v_fma_f32 v2, v2, v6, v2
	v_fma_f32 v3, v3, v7, v3
	v_fma_f32 v4, v4, v246, v4
	v_mul_f32_e32 v1, 0x3f4c422a, v1
	v_mul_f32_e32 v2, 0x3f4c422a, v2
	v_mul_f32_e32 v3, 0x3f4c422a, v3
	v_mul_f32_e32 v4, 0x3f4c422a, v4
	v_mul_f32_e32 v1, 0x4038aa3b, v1
	v_mul_f32_e32 v2, 0x4038aa3b, v2
	v_mul_f32_e32 v3, 0x4038aa3b, v3
	v_mul_f32_e32 v4, 0x4038aa3b, v4
	v_exp_f32_e32 v1, v1
	v_exp_f32_e32 v2, v2
	v_exp_f32_e32 v3, v3
	v_exp_f32_e32 v4, v4
	v_add_f32_e32 v1, 1.0, v1
	v_add_f32_e32 v2, 1.0, v2
	v_add_f32_e32 v3, 1.0, v3
	v_add_f32_e32 v4, 1.0, v4
	v_rcp_f32_e32 v1, v1
	v_rcp_f32_e32 v2, v2
	v_rcp_f32_e32 v3, v3
	v_rcp_f32_e32 v4, v4
	v_fma_f32 v1, v1, -2.0, 1.0
	v_fma_f32 v2, v2, -2.0, 1.0
	v_fma_f32 v3, v3, -2.0, 1.0
	v_fma_f32 v4, v4, -2.0, 1.0
	v_add_f32_e32 v1, 1.0, v1
	v_add_f32_e32 v2, 1.0, v2
	v_add_f32_e32 v3, 1.0, v3
	v_add_f32_e32 v4, 1.0, v4
	v_mul_f32_e32 v1, v194, v1
	v_mul_f32_e32 v2, v195, v2
	v_mul_f32_e32 v3, v196, v3
	v_mul_f32_e32 v4, v197, v4
	v_cvt_pk_bf16_f32 v1, v1, v1
	v_cvt_pk_bf16_f32 v2, v2, v2
	v_cvt_pk_bf16_f32 v3, v3, v3
	v_cvt_pk_bf16_f32 v4, v4, v4
	global_store_short v198, v1, s[28:29] offset:-4096
	global_store_short v198, v2, s[28:29] offset:-2048
	global_store_short v198, v3, s[28:29] offset:0
	global_store_short v198, v4, s[28:29] offset:2048
	s_add_u32 s26, s26, 0x400000
	s_addc_u32 s27, s27, 0
	s_xor_b32 s20, s20, 0x4000
	s_add_i32 s19, s19, 1
	s_cmp_lt_u32 s19, 8
	s_cbranch_scc1 .Ls5n_round
	s_waitcnt vmcnt(0) lgkmcnt(0)
	s_barrier
	s_branch .LBB0_727
